# v14
# speedup vs baseline: 1.0087x; 1.0062x over previous
; DI float bflo(unsigned u) { return __uint_as_float(u << 16); }
; DI float bfhi(unsigned u) { return __uint_as_float(u & 0xffff0000u); }
; DI u32x4 pk8(const f32x4 a, const f32x4 b) { return (u32x4){pk2(a[0], a[1]), pk2(a[2], a[3]), pk2(b[0], b[1]), pk2(b[2], b[3])}; }
;     MI void operator()(const f32x4 (&acc)[2][2][4][2], const Unit& u, int wr, int wc, int fr, int fq) const {
;     ...
;                 const int row = u.pm * 256 + ai * 128 + wr * 64 + m * 16 + fr; const int col = u.pn * 256 + wc * 32 + 8 * fq;
;                 bf16_t* yp = Y + (size_t)row * DM + col; const bf16_t* gp = G + (size_t)row * RESTW + col;
; #pragma unroll
;                 for (int bj = 0; bj < 2; ++bj) {
;                     const u32x4 g = *(const u32x4*)(gp + bj * 128); const f32x4 a0 = acc[ai][bj][m][0], a1 = acc[ai][bj][m][1];
;                     f32x4 v0 = (f32x4){a0[0] * bflo(g.x), a0[1] * bfhi(g.x), a0[2] * bflo(g.y), a0[3] * bfhi(g.y)}, v1 = (f32x4){a1[0] * bflo(g.z), a1[1] * bfhi(g.z), a1[2] * bflo(g.w), a1[3] * bfhi(g.w)};
;                     if (!FIRST) { const u32x4 y = *(const u32x4*)(yp + bj * 128); v0 += (f32x4){bflo(y.x), bfhi(y.x), bflo(y.y), bfhi(y.y)}; v1 += (f32x4){bflo(y.z), bfhi(y.z), bflo(y.w), bfhi(y.w)}; }
;                     *(u32x4*)(yp + bj * 128) = pk8(v0, v1);
.LBB0_638:
	v_lshl_add_u32 v140, s80, 8, v144
	v_lshl_or_b32 v138, s78, 8, v146
	v_ashrrev_i32_e32 v141, 31, v140
	v_ashrrev_i32_e32 v139, 31, v138
	v_lshlrev_b64 v[142:143], 12, v[140:141]
	v_readlane_b32 s6, v254, 24
	v_lshl_add_u64 v[142:143], s[90:91], 0, v[142:143]
	v_lshlrev_b64 v[138:139], 1, v[138:139]
	v_readlane_b32 s7, v254, 25
	v_lshl_add_u64 v[152:153], v[142:143], 0, v[138:139]
	s_andn2_b64 vcc, exec, s[4:5]
	v_mov_b64_e32 v[142:143], s[6:7]
	v_mad_i64_i32 v[148:149], s[6:7], v140, s14, v[142:143]
	v_lshl_add_u64 v[154:155], v[148:149], 0, v[138:139]
	s_mov_b64 s[82:83], s[40:41]
	v_mov_b32_e32 v150, v140
	v_ashrrev_i32_e32 v151, 31, v150
	v_lshlrev_b64 v[250:251], 12, v[150:151]
	v_mad_i64_i32 v[182:183], s[6:7], v150, s14, v[142:143]
	v_lshl_add_u64 v[250:251], s[90:91], 0, v[250:251]
	v_lshl_add_u64 v[182:183], v[182:183], 0, v[138:139]
	v_lshl_add_u64 v[250:251], v[250:251], 0, v[138:139]
	global_load_dwordx4 v[166:169], v[182:183], off
	global_load_dwordx4 v[170:173], v[182:183], off offset:256
	v_add_u32_e32 v150, 0x10, v140
	v_ashrrev_i32_e32 v151, 31, v150
	v_lshlrev_b64 v[242:243], 12, v[150:151]
	v_mad_i64_i32 v[218:219], s[6:7], v150, s14, v[142:143]
	v_lshl_add_u64 v[242:243], s[90:91], 0, v[242:243]
	v_lshl_add_u64 v[218:219], v[218:219], 0, v[138:139]
	v_lshl_add_u64 v[242:243], v[242:243], 0, v[138:139]
	global_load_dwordx4 v[174:177], v[218:219], off
	global_load_dwordx4 v[178:181], v[218:219], off offset:256
	v_add_u32_e32 v150, 0x20, v140
	v_ashrrev_i32_e32 v151, 31, v150
	v_lshlrev_b64 v[246:247], 12, v[150:151]
	v_mad_i64_i32 v[244:245], s[6:7], v150, s14, v[142:143]
	v_lshl_add_u64 v[246:247], s[90:91], 0, v[246:247]
	v_lshl_add_u64 v[244:245], v[244:245], 0, v[138:139]
	v_lshl_add_u64 v[246:247], v[246:247], 0, v[138:139]
	global_load_dwordx4 v[186:189], v[244:245], off
	global_load_dwordx4 v[190:193], v[244:245], off offset:256
	s_waitcnt vmcnt(4)
	v_lshlrev_b32_e32 v150, 16, v166
	v_and_b32_e32 v151, 0xffff0000, v166
	v_lshlrev_b32_e32 v152, 16, v167
	v_and_b32_e32 v153, 0xffff0000, v167
	v_lshlrev_b32_e32 v154, 16, v168
	v_and_b32_e32 v155, 0xffff0000, v168
	v_lshlrev_b32_e32 v156, 16, v169
	v_and_b32_e32 v157, 0xffff0000, v169
	v_pk_mul_f32 v[124:125], v[124:125], v[150:151]
	v_pk_mul_f32 v[126:127], v[126:127], v[152:153]
	v_pk_mul_f32 v[158:159], v[120:121], v[154:155]
	v_pk_mul_f32 v[160:161], v[122:123], v[156:157]
	v_cvt_pk_bf16_f32 v120, v124, v125
	v_cvt_pk_bf16_f32 v121, v126, v127
	v_cvt_pk_bf16_f32 v122, v158, v159
	v_cvt_pk_bf16_f32 v123, v160, v161
	global_store_dwordx4 v[250:251], v[120:123], off
	v_lshlrev_b32_e32 v150, 16, v170
	v_and_b32_e32 v151, 0xffff0000, v170
	v_lshlrev_b32_e32 v152, 16, v171
	v_and_b32_e32 v153, 0xffff0000, v171
	v_lshlrev_b32_e32 v154, 16, v172
	v_and_b32_e32 v155, 0xffff0000, v172
	v_lshlrev_b32_e32 v156, 16, v173
	v_and_b32_e32 v157, 0xffff0000, v173
	v_pk_mul_f32 v[116:117], v[116:117], v[150:151]
	v_pk_mul_f32 v[118:119], v[118:119], v[152:153]
	v_pk_mul_f32 v[158:159], v[112:113], v[154:155]
	v_pk_mul_f32 v[160:161], v[114:115], v[156:157]
	v_cvt_pk_bf16_f32 v112, v116, v117
	v_cvt_pk_bf16_f32 v113, v118, v119
	v_cvt_pk_bf16_f32 v114, v158, v159
	v_cvt_pk_bf16_f32 v115, v160, v161
	global_store_dwordx4 v[250:251], v[112:115], off offset:256
	s_nop 1
	v_add_u32_e32 v150, 0x30, v140
	v_ashrrev_i32_e32 v151, 31, v150
	v_lshlrev_b64 v[250:251], 12, v[150:151]
	v_mad_i64_i32 v[182:183], s[6:7], v150, s14, v[142:143]
	v_lshl_add_u64 v[250:251], s[90:91], 0, v[250:251]
	v_lshl_add_u64 v[182:183], v[182:183], 0, v[138:139]
	v_lshl_add_u64 v[250:251], v[250:251], 0, v[138:139]
	global_load_dwordx4 v[166:169], v[182:183], off
	global_load_dwordx4 v[170:173], v[182:183], off offset:256
	s_waitcnt vmcnt(6)
	v_lshlrev_b32_e32 v150, 16, v174
	v_and_b32_e32 v151, 0xffff0000, v174
	v_lshlrev_b32_e32 v152, 16, v175
	v_and_b32_e32 v153, 0xffff0000, v175
	v_lshlrev_b32_e32 v154, 16, v176
	v_and_b32_e32 v155, 0xffff0000, v176
	v_lshlrev_b32_e32 v156, 16, v177
	v_and_b32_e32 v157, 0xffff0000, v177
	v_pk_mul_f32 v[108:109], v[108:109], v[150:151]
	v_pk_mul_f32 v[110:111], v[110:111], v[152:153]
	v_pk_mul_f32 v[158:159], v[104:105], v[154:155]
	v_pk_mul_f32 v[160:161], v[106:107], v[156:157]
	v_cvt_pk_bf16_f32 v104, v108, v109
	v_cvt_pk_bf16_f32 v105, v110, v111
	v_cvt_pk_bf16_f32 v106, v158, v159
	v_cvt_pk_bf16_f32 v107, v160, v161
	global_store_dwordx4 v[242:243], v[104:107], off
	v_lshlrev_b32_e32 v150, 16, v178
	v_and_b32_e32 v151, 0xffff0000, v178
	v_lshlrev_b32_e32 v152, 16, v179
	v_and_b32_e32 v153, 0xffff0000, v179
	v_lshlrev_b32_e32 v154, 16, v180
	v_and_b32_e32 v155, 0xffff0000, v180
	v_lshlrev_b32_e32 v156, 16, v181
	v_and_b32_e32 v157, 0xffff0000, v181
	v_pk_mul_f32 v[100:101], v[100:101], v[150:151]
	v_pk_mul_f32 v[102:103], v[102:103], v[152:153]
	v_pk_mul_f32 v[158:159], v[96:97], v[154:155]
	v_pk_mul_f32 v[160:161], v[98:99], v[156:157]
	v_cvt_pk_bf16_f32 v96, v100, v101
	v_cvt_pk_bf16_f32 v97, v102, v103
	v_cvt_pk_bf16_f32 v98, v158, v159
	v_cvt_pk_bf16_f32 v99, v160, v161
	global_store_dwordx4 v[242:243], v[96:99], off offset:256
	s_nop 1
	v_add_u32_e32 v150, 0x80, v140
	v_ashrrev_i32_e32 v151, 31, v150
	v_lshlrev_b64 v[242:243], 12, v[150:151]
	v_mad_i64_i32 v[218:219], s[6:7], v150, s14, v[142:143]
	v_lshl_add_u64 v[242:243], s[90:91], 0, v[242:243]
	v_lshl_add_u64 v[218:219], v[218:219], 0, v[138:139]
	v_lshl_add_u64 v[242:243], v[242:243], 0, v[138:139]
	global_load_dwordx4 v[174:177], v[218:219], off
	global_load_dwordx4 v[178:181], v[218:219], off offset:256
	s_waitcnt vmcnt(8)
; DI float bflo(unsigned u) { return __uint_as_float(u << 16); }
; DI float bfhi(unsigned u) { return __uint_as_float(u & 0xffff0000u); }
; DI u32x4 pk8(const f32x4 a, const f32x4 b) { return (u32x4){pk2(a[0], a[1]), pk2(a[2], a[3]), pk2(b[0], b[1]), pk2(b[2], b[3])}; }
;     MI void operator()(const f32x4 (&acc)[2][2][4][2], const Unit& u, int wr, int wc, int fr, int fq) const {
;     ...
;                 const int row = u.pm * 256 + ai * 128 + wr * 64 + m * 16 + fr; const int col = u.pn * 256 + wc * 32 + 8 * fq;
;                 bf16_t* yp = Y + (size_t)row * DM + col; const bf16_t* gp = G + (size_t)row * RESTW + col;
; #pragma unroll
;                 for (int bj = 0; bj < 2; ++bj) {
;                     const u32x4 g = *(const u32x4*)(gp + bj * 128); const f32x4 a0 = acc[ai][bj][m][0], a1 = acc[ai][bj][m][1];
;                     f32x4 v0 = (f32x4){a0[0] * bflo(g.x), a0[1] * bfhi(g.x), a0[2] * bflo(g.y), a0[3] * bfhi(g.y)}, v1 = (f32x4){a1[0] * bflo(g.z), a1[1] * bfhi(g.z), a1[2] * bflo(g.w), a1[3] * bfhi(g.w)};
;                     if (!FIRST) { const u32x4 y = *(const u32x4*)(yp + bj * 128); v0 += (f32x4){bflo(y.x), bfhi(y.x), bflo(y.y), bfhi(y.y)}; v1 += (f32x4){bflo(y.z), bfhi(y.z), bflo(y.w), bfhi(y.w)}; }
;                     *(u32x4*)(yp + bj * 128) = pk8(v0, v1);
	v_lshlrev_b32_e32 v150, 16, v186
	v_and_b32_e32 v151, 0xffff0000, v186
	v_lshlrev_b32_e32 v152, 16, v187
	v_and_b32_e32 v153, 0xffff0000, v187
	v_lshlrev_b32_e32 v154, 16, v188
	v_and_b32_e32 v155, 0xffff0000, v188
	v_lshlrev_b32_e32 v156, 16, v189
	v_and_b32_e32 v157, 0xffff0000, v189
	v_pk_mul_f32 v[92:93], v[92:93], v[150:151]
	v_pk_mul_f32 v[94:95], v[94:95], v[152:153]
	v_pk_mul_f32 v[158:159], v[88:89], v[154:155]
	v_pk_mul_f32 v[160:161], v[90:91], v[156:157]
	v_cvt_pk_bf16_f32 v88, v92, v93
	v_cvt_pk_bf16_f32 v89, v94, v95
	v_cvt_pk_bf16_f32 v90, v158, v159
	v_cvt_pk_bf16_f32 v91, v160, v161
	global_store_dwordx4 v[246:247], v[88:91], off
	v_lshlrev_b32_e32 v150, 16, v190
	v_and_b32_e32 v151, 0xffff0000, v190
	v_lshlrev_b32_e32 v152, 16, v191
	v_and_b32_e32 v153, 0xffff0000, v191
	v_lshlrev_b32_e32 v154, 16, v192
	v_and_b32_e32 v155, 0xffff0000, v192
	v_lshlrev_b32_e32 v156, 16, v193
	v_and_b32_e32 v157, 0xffff0000, v193
	v_pk_mul_f32 v[84:85], v[84:85], v[150:151]
	v_pk_mul_f32 v[86:87], v[86:87], v[152:153]
	v_pk_mul_f32 v[158:159], v[80:81], v[154:155]
	v_pk_mul_f32 v[160:161], v[82:83], v[156:157]
	v_cvt_pk_bf16_f32 v80, v84, v85
	v_cvt_pk_bf16_f32 v81, v86, v87
	v_cvt_pk_bf16_f32 v82, v158, v159
	v_cvt_pk_bf16_f32 v83, v160, v161
	global_store_dwordx4 v[246:247], v[80:83], off offset:256
	s_nop 1
	v_add_u32_e32 v150, 0x90, v140
	v_ashrrev_i32_e32 v151, 31, v150
	v_lshlrev_b64 v[246:247], 12, v[150:151]
	v_mad_i64_i32 v[244:245], s[6:7], v150, s14, v[142:143]
	v_lshl_add_u64 v[246:247], s[90:91], 0, v[246:247]
	v_lshl_add_u64 v[244:245], v[244:245], 0, v[138:139]
	v_lshl_add_u64 v[246:247], v[246:247], 0, v[138:139]
	global_load_dwordx4 v[186:189], v[244:245], off
	global_load_dwordx4 v[190:193], v[244:245], off offset:256
	s_waitcnt vmcnt(8)
	v_lshlrev_b32_e32 v150, 16, v166
	v_and_b32_e32 v151, 0xffff0000, v166
	v_lshlrev_b32_e32 v152, 16, v167
	v_and_b32_e32 v153, 0xffff0000, v167
	v_lshlrev_b32_e32 v154, 16, v168
	v_and_b32_e32 v155, 0xffff0000, v168
	v_lshlrev_b32_e32 v156, 16, v169
	v_and_b32_e32 v157, 0xffff0000, v169
	v_pk_mul_f32 v[76:77], v[76:77], v[150:151]
	v_pk_mul_f32 v[78:79], v[78:79], v[152:153]
	v_pk_mul_f32 v[158:159], v[72:73], v[154:155]
	v_pk_mul_f32 v[160:161], v[74:75], v[156:157]
	v_cvt_pk_bf16_f32 v72, v76, v77
	v_cvt_pk_bf16_f32 v73, v78, v79
	v_cvt_pk_bf16_f32 v74, v158, v159
	v_cvt_pk_bf16_f32 v75, v160, v161
	global_store_dwordx4 v[250:251], v[72:75], off
	v_lshlrev_b32_e32 v150, 16, v170
	v_and_b32_e32 v151, 0xffff0000, v170
	v_lshlrev_b32_e32 v152, 16, v171
	v_and_b32_e32 v153, 0xffff0000, v171
	v_lshlrev_b32_e32 v154, 16, v172
	v_and_b32_e32 v155, 0xffff0000, v172
	v_lshlrev_b32_e32 v156, 16, v173
	v_and_b32_e32 v157, 0xffff0000, v173
	v_pk_mul_f32 v[68:69], v[68:69], v[150:151]
	v_pk_mul_f32 v[70:71], v[70:71], v[152:153]
	v_pk_mul_f32 v[158:159], v[64:65], v[154:155]
	v_pk_mul_f32 v[160:161], v[66:67], v[156:157]
	v_cvt_pk_bf16_f32 v64, v68, v69
	v_cvt_pk_bf16_f32 v65, v70, v71
	v_cvt_pk_bf16_f32 v66, v158, v159
	v_cvt_pk_bf16_f32 v67, v160, v161
	global_store_dwordx4 v[250:251], v[64:67], off offset:256
	s_nop 1
	v_add_u32_e32 v150, 0xa0, v140
	v_ashrrev_i32_e32 v151, 31, v150
	v_lshlrev_b64 v[250:251], 12, v[150:151]
	v_mad_i64_i32 v[182:183], s[6:7], v150, s14, v[142:143]
	v_lshl_add_u64 v[250:251], s[90:91], 0, v[250:251]
	v_lshl_add_u64 v[182:183], v[182:183], 0, v[138:139]
	v_lshl_add_u64 v[250:251], v[250:251], 0, v[138:139]
	global_load_dwordx4 v[166:169], v[182:183], off
	global_load_dwordx4 v[170:173], v[182:183], off offset:256
	s_waitcnt vmcnt(8)
	v_lshlrev_b32_e32 v150, 16, v174
	v_and_b32_e32 v151, 0xffff0000, v174
	v_lshlrev_b32_e32 v152, 16, v175
	v_and_b32_e32 v153, 0xffff0000, v175
	v_lshlrev_b32_e32 v154, 16, v176
	v_and_b32_e32 v155, 0xffff0000, v176
	v_lshlrev_b32_e32 v156, 16, v177
	v_and_b32_e32 v157, 0xffff0000, v177
	v_pk_mul_f32 v[60:61], v[60:61], v[150:151]
	v_pk_mul_f32 v[62:63], v[62:63], v[152:153]
	v_pk_mul_f32 v[158:159], v[56:57], v[154:155]
	v_pk_mul_f32 v[160:161], v[58:59], v[156:157]
	v_cvt_pk_bf16_f32 v56, v60, v61
	v_cvt_pk_bf16_f32 v57, v62, v63
	v_cvt_pk_bf16_f32 v58, v158, v159
	v_cvt_pk_bf16_f32 v59, v160, v161
	global_store_dwordx4 v[242:243], v[56:59], off
	v_lshlrev_b32_e32 v150, 16, v178
	v_and_b32_e32 v151, 0xffff0000, v178
	v_lshlrev_b32_e32 v152, 16, v179
	v_and_b32_e32 v153, 0xffff0000, v179
	v_lshlrev_b32_e32 v154, 16, v180
	v_and_b32_e32 v155, 0xffff0000, v180
	v_lshlrev_b32_e32 v156, 16, v181
	v_and_b32_e32 v157, 0xffff0000, v181
	v_pk_mul_f32 v[52:53], v[52:53], v[150:151]
	v_pk_mul_f32 v[54:55], v[54:55], v[152:153]
	v_pk_mul_f32 v[158:159], v[48:49], v[154:155]
	v_pk_mul_f32 v[160:161], v[50:51], v[156:157]
	v_cvt_pk_bf16_f32 v48, v52, v53
	v_cvt_pk_bf16_f32 v49, v54, v55
	v_cvt_pk_bf16_f32 v50, v158, v159
	v_cvt_pk_bf16_f32 v51, v160, v161
	global_store_dwordx4 v[242:243], v[48:51], off offset:256
	s_nop 1
	v_add_u32_e32 v150, 0xb0, v140
	v_ashrrev_i32_e32 v151, 31, v150
	v_lshlrev_b64 v[242:243], 12, v[150:151]
	v_mad_i64_i32 v[218:219], s[6:7], v150, s14, v[142:143]
	v_lshl_add_u64 v[242:243], s[90:91], 0, v[242:243]
	v_lshl_add_u64 v[218:219], v[218:219], 0, v[138:139]
	v_lshl_add_u64 v[242:243], v[242:243], 0, v[138:139]
	global_load_dwordx4 v[174:177], v[218:219], off
	global_load_dwordx4 v[178:181], v[218:219], off offset:256
	s_waitcnt vmcnt(8)
; DI float bflo(unsigned u) { return __uint_as_float(u << 16); }
; DI float bfhi(unsigned u) { return __uint_as_float(u & 0xffff0000u); }
; DI u32x4 pk8(const f32x4 a, const f32x4 b) { return (u32x4){pk2(a[0], a[1]), pk2(a[2], a[3]), pk2(b[0], b[1]), pk2(b[2], b[3])}; }
;     MI void operator()(const f32x4 (&acc)[2][2][4][2], const Unit& u, int wr, int wc, int fr, int fq) const {
;     ...
;                 const int row = u.pm * 256 + ai * 128 + wr * 64 + m * 16 + fr; const int col = u.pn * 256 + wc * 32 + 8 * fq;
;                 bf16_t* yp = Y + (size_t)row * DM + col; const bf16_t* gp = G + (size_t)row * RESTW + col;
; #pragma unroll
;                 for (int bj = 0; bj < 2; ++bj) {
;                     const u32x4 g = *(const u32x4*)(gp + bj * 128); const f32x4 a0 = acc[ai][bj][m][0], a1 = acc[ai][bj][m][1];
;                     f32x4 v0 = (f32x4){a0[0] * bflo(g.x), a0[1] * bfhi(g.x), a0[2] * bflo(g.y), a0[3] * bfhi(g.y)}, v1 = (f32x4){a1[0] * bflo(g.z), a1[1] * bfhi(g.z), a1[2] * bflo(g.w), a1[3] * bfhi(g.w)};
;                     if (!FIRST) { const u32x4 y = *(const u32x4*)(yp + bj * 128); v0 += (f32x4){bflo(y.x), bfhi(y.x), bflo(y.y), bfhi(y.y)}; v1 += (f32x4){bflo(y.z), bfhi(y.z), bflo(y.w), bfhi(y.w)}; }
;                     *(u32x4*)(yp + bj * 128) = pk8(v0, v1);
	v_lshlrev_b32_e32 v150, 16, v186
	v_and_b32_e32 v151, 0xffff0000, v186
	v_lshlrev_b32_e32 v152, 16, v187
	v_and_b32_e32 v153, 0xffff0000, v187
	v_lshlrev_b32_e32 v154, 16, v188
	v_and_b32_e32 v155, 0xffff0000, v188
	v_lshlrev_b32_e32 v156, 16, v189
	v_and_b32_e32 v157, 0xffff0000, v189
	v_pk_mul_f32 v[44:45], v[44:45], v[150:151]
	v_pk_mul_f32 v[46:47], v[46:47], v[152:153]
	v_pk_mul_f32 v[158:159], v[40:41], v[154:155]
	v_pk_mul_f32 v[160:161], v[42:43], v[156:157]
	v_cvt_pk_bf16_f32 v40, v44, v45
	v_cvt_pk_bf16_f32 v41, v46, v47
	v_cvt_pk_bf16_f32 v42, v158, v159
	v_cvt_pk_bf16_f32 v43, v160, v161
	global_store_dwordx4 v[246:247], v[40:43], off
	v_lshlrev_b32_e32 v150, 16, v190
	v_and_b32_e32 v151, 0xffff0000, v190
	v_lshlrev_b32_e32 v152, 16, v191
	v_and_b32_e32 v153, 0xffff0000, v191
	v_lshlrev_b32_e32 v154, 16, v192
	v_and_b32_e32 v155, 0xffff0000, v192
	v_lshlrev_b32_e32 v156, 16, v193
	v_and_b32_e32 v157, 0xffff0000, v193
	v_pk_mul_f32 v[36:37], v[36:37], v[150:151]
	v_pk_mul_f32 v[38:39], v[38:39], v[152:153]
	v_pk_mul_f32 v[158:159], v[32:33], v[154:155]
	v_pk_mul_f32 v[160:161], v[34:35], v[156:157]
	v_cvt_pk_bf16_f32 v32, v36, v37
	v_cvt_pk_bf16_f32 v33, v38, v39
	v_cvt_pk_bf16_f32 v34, v158, v159
	v_cvt_pk_bf16_f32 v35, v160, v161
	global_store_dwordx4 v[246:247], v[32:35], off offset:256
	s_waitcnt vmcnt(6)
	v_lshlrev_b32_e32 v150, 16, v166
	v_and_b32_e32 v151, 0xffff0000, v166
	v_lshlrev_b32_e32 v152, 16, v167
	v_and_b32_e32 v153, 0xffff0000, v167
	v_lshlrev_b32_e32 v154, 16, v168
	v_and_b32_e32 v155, 0xffff0000, v168
	v_lshlrev_b32_e32 v156, 16, v169
	v_and_b32_e32 v157, 0xffff0000, v169
	v_pk_mul_f32 v[28:29], v[28:29], v[150:151]
	v_pk_mul_f32 v[30:31], v[30:31], v[152:153]
	v_pk_mul_f32 v[158:159], v[24:25], v[154:155]
	v_pk_mul_f32 v[160:161], v[26:27], v[156:157]
	v_cvt_pk_bf16_f32 v24, v28, v29
	v_cvt_pk_bf16_f32 v25, v30, v31
	v_cvt_pk_bf16_f32 v26, v158, v159
	v_cvt_pk_bf16_f32 v27, v160, v161
	global_store_dwordx4 v[250:251], v[24:27], off
	v_lshlrev_b32_e32 v150, 16, v170
	v_and_b32_e32 v151, 0xffff0000, v170
	v_lshlrev_b32_e32 v152, 16, v171
	v_and_b32_e32 v153, 0xffff0000, v171
	v_lshlrev_b32_e32 v154, 16, v172
	v_and_b32_e32 v155, 0xffff0000, v172
	v_lshlrev_b32_e32 v156, 16, v173
	v_and_b32_e32 v157, 0xffff0000, v173
	v_pk_mul_f32 v[20:21], v[20:21], v[150:151]
	v_pk_mul_f32 v[22:23], v[22:23], v[152:153]
	v_pk_mul_f32 v[158:159], v[16:17], v[154:155]
	v_pk_mul_f32 v[160:161], v[18:19], v[156:157]
	v_cvt_pk_bf16_f32 v16, v20, v21
	v_cvt_pk_bf16_f32 v17, v22, v23
	v_cvt_pk_bf16_f32 v18, v158, v159
	v_cvt_pk_bf16_f32 v19, v160, v161
	global_store_dwordx4 v[250:251], v[16:19], off offset:256
	s_waitcnt vmcnt(4)
	v_lshlrev_b32_e32 v150, 16, v174
	v_and_b32_e32 v151, 0xffff0000, v174
	v_lshlrev_b32_e32 v152, 16, v175
	v_and_b32_e32 v153, 0xffff0000, v175
	v_lshlrev_b32_e32 v154, 16, v176
	v_and_b32_e32 v155, 0xffff0000, v176
	v_lshlrev_b32_e32 v156, 16, v177
	v_and_b32_e32 v157, 0xffff0000, v177
	v_pk_mul_f32 v[12:13], v[12:13], v[150:151]
	v_pk_mul_f32 v[14:15], v[14:15], v[152:153]
	v_pk_mul_f32 v[158:159], v[8:9], v[154:155]
	v_pk_mul_f32 v[160:161], v[10:11], v[156:157]
	v_cvt_pk_bf16_f32 v8, v12, v13
	v_cvt_pk_bf16_f32 v9, v14, v15
	v_cvt_pk_bf16_f32 v10, v158, v159
	v_cvt_pk_bf16_f32 v11, v160, v161
	global_store_dwordx4 v[242:243], v[8:11], off
	v_lshlrev_b32_e32 v150, 16, v178
	v_and_b32_e32 v151, 0xffff0000, v178
	v_lshlrev_b32_e32 v152, 16, v179
	v_and_b32_e32 v153, 0xffff0000, v179
	v_lshlrev_b32_e32 v154, 16, v180
	v_and_b32_e32 v155, 0xffff0000, v180
	v_lshlrev_b32_e32 v156, 16, v181
	v_and_b32_e32 v157, 0xffff0000, v181
	v_pk_mul_f32 v[4:5], v[4:5], v[150:151]
	v_pk_mul_f32 v[6:7], v[6:7], v[152:153]
	v_pk_mul_f32 v[158:159], v[0:1], v[154:155]
	v_pk_mul_f32 v[160:161], v[2:3], v[156:157]
	v_cvt_pk_bf16_f32 v0, v4, v5
	v_cvt_pk_bf16_f32 v1, v6, v7
	v_cvt_pk_bf16_f32 v2, v158, v159
	v_cvt_pk_bf16_f32 v3, v160, v161
	global_store_dwordx4 v[242:243], v[0:3], off offset:256
	s_mov_b64 s[6:7], -1
	s_cbranch_vccnz .LBB0_631
	s_andn2_b64 vcc, exec, s[8:9]
	s_cbranch_vccnz .LBB0_630
	s_barrier
	s_branch .LBB0_630

; DI float bflo(unsigned u) { return __uint_as_float(u << 16); }
; DI float bfhi(unsigned u) { return __uint_as_float(u & 0xffff0000u); }
; DI u32x4 pk8(const f32x4 a, const f32x4 b) { return (u32x4){pk2(a[0], a[1]), pk2(a[2], a[3]), pk2(b[0], b[1]), pk2(b[2], b[3])}; }
;     MI void operator()(const f32x4 (&acc)[2][2][4][2], const Unit& u, int wr, int wc, int fr, int fq) const {
;     ...
;                 const int row = u.pm * 256 + ai * 128 + wr * 64 + m * 16 + fr; const int col = u.pn * 256 + wc * 32 + 8 * fq;
;                 bf16_t* yp = Y + (size_t)row * DM + col; const bf16_t* gp = G + (size_t)row * RESTW + col;
; #pragma unroll
;                 for (int bj = 0; bj < 2; ++bj) {
;                     const u32x4 g = *(const u32x4*)(gp + bj * 128); const f32x4 a0 = acc[ai][bj][m][0], a1 = acc[ai][bj][m][1];
;                     f32x4 v0 = (f32x4){a0[0] * bflo(g.x), a0[1] * bfhi(g.x), a0[2] * bflo(g.y), a0[3] * bfhi(g.y)}, v1 = (f32x4){a1[0] * bflo(g.z), a1[1] * bfhi(g.z), a1[2] * bflo(g.w), a1[3] * bfhi(g.w)};
;                     if (!FIRST) { const u32x4 y = *(const u32x4*)(yp + bj * 128); v0 += (f32x4){bflo(y.x), bfhi(y.x), bflo(y.y), bfhi(y.y)}; v1 += (f32x4){bflo(y.z), bfhi(y.z), bflo(y.w), bfhi(y.w)}; }
;                     *(u32x4*)(yp + bj * 128) = pk8(v0, v1);
.LBB0_654:
	v_lshl_add_u32 v140, s80, 8, v146
	v_lshl_or_b32 v138, s78, 8, v148
	v_ashrrev_i32_e32 v141, 31, v140
	v_ashrrev_i32_e32 v139, 31, v138
	v_lshlrev_b64 v[142:143], 12, v[140:141]
	v_readlane_b32 s6, v254, 26
	v_lshl_add_u64 v[142:143], s[90:91], 0, v[142:143]
	v_lshlrev_b64 v[138:139], 1, v[138:139]
	v_readlane_b32 s7, v254, 27
	v_lshl_add_u64 v[144:145], v[142:143], 0, v[138:139]
	s_mov_b64 s[78:79], -1
	v_mov_b64_e32 v[142:143], s[6:7]
	v_mad_i64_i32 v[150:151], s[6:7], v140, s14, v[142:143]
	v_lshl_add_u64 v[154:155], v[150:151], 0, v[138:139]
	s_andn2_b64 vcc, exec, s[4:5]
	s_mov_b64 s[82:83], s[40:41]
	v_mov_b32_e32 v150, v140
	v_ashrrev_i32_e32 v151, 31, v150
	v_lshlrev_b64 v[250:251], 12, v[150:151]
	v_mad_i64_i32 v[182:183], s[6:7], v150, s14, v[142:143]
	v_lshl_add_u64 v[250:251], s[90:91], 0, v[250:251]
	v_lshl_add_u64 v[182:183], v[182:183], 0, v[138:139]
	v_lshl_add_u64 v[250:251], v[250:251], 0, v[138:139]
	global_load_dwordx4 v[166:169], v[182:183], off
	global_load_dwordx4 v[170:173], v[250:251], off
	global_load_dwordx4 v[174:177], v[182:183], off offset:256
	global_load_dwordx4 v[178:181], v[250:251], off offset:256
	v_add_u32_e32 v150, 0x10, v140
	v_ashrrev_i32_e32 v151, 31, v150
	v_lshlrev_b64 v[242:243], 12, v[150:151]
	v_mad_i64_i32 v[218:219], s[6:7], v150, s14, v[142:143]
	v_lshl_add_u64 v[242:243], s[90:91], 0, v[242:243]
	v_lshl_add_u64 v[218:219], v[218:219], 0, v[138:139]
	v_lshl_add_u64 v[242:243], v[242:243], 0, v[138:139]
	global_load_dwordx4 v[186:189], v[218:219], off
	global_load_dwordx4 v[190:193], v[242:243], off
	global_load_dwordx4 v[194:197], v[218:219], off offset:256
	global_load_dwordx4 v[222:225], v[242:243], off offset:256
	v_add_u32_e32 v150, 0x20, v140
	v_ashrrev_i32_e32 v151, 31, v150
	v_lshlrev_b64 v[246:247], 12, v[150:151]
	v_mad_i64_i32 v[244:245], s[6:7], v150, s14, v[142:143]
	v_lshl_add_u64 v[246:247], s[90:91], 0, v[246:247]
	v_lshl_add_u64 v[244:245], v[244:245], 0, v[138:139]
	v_lshl_add_u64 v[246:247], v[246:247], 0, v[138:139]
	global_load_dwordx4 v[226:229], v[244:245], off
	global_load_dwordx4 v[230:233], v[246:247], off
	global_load_dwordx4 v[234:237], v[244:245], off offset:256
	global_load_dwordx4 v[238:241], v[246:247], off offset:256
	s_waitcnt vmcnt(8)
	v_lshlrev_b32_e32 v150, 16, v166
	v_and_b32_e32 v151, 0xffff0000, v166
	v_lshlrev_b32_e32 v152, 16, v167
	v_and_b32_e32 v153, 0xffff0000, v167
	v_lshlrev_b32_e32 v154, 16, v168
	v_and_b32_e32 v155, 0xffff0000, v168
	v_lshlrev_b32_e32 v156, 16, v169
	v_and_b32_e32 v157, 0xffff0000, v169
	v_lshlrev_b32_e32 v158, 16, v170
	v_and_b32_e32 v159, 0xffff0000, v170
	v_lshlrev_b32_e32 v160, 16, v171
	v_and_b32_e32 v161, 0xffff0000, v171
	v_lshlrev_b32_e32 v162, 16, v172
	v_and_b32_e32 v163, 0xffff0000, v172
	v_lshlrev_b32_e32 v164, 16, v173
	v_and_b32_e32 v165, 0xffff0000, v173
	v_pk_fma_f32 v[124:125], v[124:125], v[150:151], v[158:159]
	v_pk_fma_f32 v[126:127], v[126:127], v[152:153], v[160:161]
	v_pk_fma_f32 v[164:165], v[122:123], v[156:157], v[164:165]
	v_pk_fma_f32 v[122:123], v[120:121], v[154:155], v[162:163]
	v_cvt_pk_bf16_f32 v120, v124, v125
	v_cvt_pk_bf16_f32 v121, v126, v127
	v_cvt_pk_bf16_f32 v122, v122, v123
	v_cvt_pk_bf16_f32 v123, v164, v165
	global_store_dwordx4 v[250:251], v[120:123], off
	v_lshlrev_b32_e32 v150, 16, v174
	v_and_b32_e32 v151, 0xffff0000, v174
	v_lshlrev_b32_e32 v152, 16, v175
	v_and_b32_e32 v153, 0xffff0000, v175
	v_lshlrev_b32_e32 v154, 16, v176
	v_and_b32_e32 v155, 0xffff0000, v176
	v_lshlrev_b32_e32 v156, 16, v177
	v_and_b32_e32 v157, 0xffff0000, v177
	v_lshlrev_b32_e32 v158, 16, v178
	v_and_b32_e32 v159, 0xffff0000, v178
	v_lshlrev_b32_e32 v160, 16, v179
	v_and_b32_e32 v161, 0xffff0000, v179
	v_lshlrev_b32_e32 v162, 16, v180
	v_and_b32_e32 v163, 0xffff0000, v180
	v_lshlrev_b32_e32 v164, 16, v181
	v_and_b32_e32 v165, 0xffff0000, v181
	v_pk_fma_f32 v[116:117], v[116:117], v[150:151], v[158:159]
	v_pk_fma_f32 v[118:119], v[118:119], v[152:153], v[160:161]
	v_pk_fma_f32 v[164:165], v[114:115], v[156:157], v[164:165]
	v_pk_fma_f32 v[114:115], v[112:113], v[154:155], v[162:163]
	v_cvt_pk_bf16_f32 v112, v116, v117
	v_cvt_pk_bf16_f32 v113, v118, v119
	v_cvt_pk_bf16_f32 v114, v114, v115
	v_cvt_pk_bf16_f32 v115, v164, v165
	global_store_dwordx4 v[250:251], v[112:115], off offset:256
	s_nop 1
	v_add_u32_e32 v150, 0x30, v140
	v_ashrrev_i32_e32 v151, 31, v150
	v_lshlrev_b64 v[250:251], 12, v[150:151]
	v_mad_i64_i32 v[182:183], s[6:7], v150, s14, v[142:143]
	v_lshl_add_u64 v[250:251], s[90:91], 0, v[250:251]
	v_lshl_add_u64 v[182:183], v[182:183], 0, v[138:139]
	v_lshl_add_u64 v[250:251], v[250:251], 0, v[138:139]
	global_load_dwordx4 v[166:169], v[182:183], off
	global_load_dwordx4 v[170:173], v[250:251], off
	global_load_dwordx4 v[174:177], v[182:183], off offset:256
	global_load_dwordx4 v[178:181], v[250:251], off offset:256
	s_waitcnt vmcnt(10)
; DI float bflo(unsigned u) { return __uint_as_float(u << 16); }
; DI float bfhi(unsigned u) { return __uint_as_float(u & 0xffff0000u); }
; DI u32x4 pk8(const f32x4 a, const f32x4 b) { return (u32x4){pk2(a[0], a[1]), pk2(a[2], a[3]), pk2(b[0], b[1]), pk2(b[2], b[3])}; }
;     MI void operator()(const f32x4 (&acc)[2][2][4][2], const Unit& u, int wr, int wc, int fr, int fq) const {
;     ...
;                 const int row = u.pm * 256 + ai * 128 + wr * 64 + m * 16 + fr; const int col = u.pn * 256 + wc * 32 + 8 * fq;
;                 bf16_t* yp = Y + (size_t)row * DM + col; const bf16_t* gp = G + (size_t)row * RESTW + col;
; #pragma unroll
;                 for (int bj = 0; bj < 2; ++bj) {
;                     const u32x4 g = *(const u32x4*)(gp + bj * 128); const f32x4 a0 = acc[ai][bj][m][0], a1 = acc[ai][bj][m][1];
;                     f32x4 v0 = (f32x4){a0[0] * bflo(g.x), a0[1] * bfhi(g.x), a0[2] * bflo(g.y), a0[3] * bfhi(g.y)}, v1 = (f32x4){a1[0] * bflo(g.z), a1[1] * bfhi(g.z), a1[2] * bflo(g.w), a1[3] * bfhi(g.w)};
;                     if (!FIRST) { const u32x4 y = *(const u32x4*)(yp + bj * 128); v0 += (f32x4){bflo(y.x), bfhi(y.x), bflo(y.y), bfhi(y.y)}; v1 += (f32x4){bflo(y.z), bfhi(y.z), bflo(y.w), bfhi(y.w)}; }
;                     *(u32x4*)(yp + bj * 128) = pk8(v0, v1);
	v_lshlrev_b32_e32 v150, 16, v186
	v_and_b32_e32 v151, 0xffff0000, v186
	v_lshlrev_b32_e32 v152, 16, v187
	v_and_b32_e32 v153, 0xffff0000, v187
	v_lshlrev_b32_e32 v154, 16, v188
	v_and_b32_e32 v155, 0xffff0000, v188
	v_lshlrev_b32_e32 v156, 16, v189
	v_and_b32_e32 v157, 0xffff0000, v189
	v_lshlrev_b32_e32 v158, 16, v190
	v_and_b32_e32 v159, 0xffff0000, v190
	v_lshlrev_b32_e32 v160, 16, v191
	v_and_b32_e32 v161, 0xffff0000, v191
	v_lshlrev_b32_e32 v162, 16, v192
	v_and_b32_e32 v163, 0xffff0000, v192
	v_lshlrev_b32_e32 v164, 16, v193
	v_and_b32_e32 v165, 0xffff0000, v193
	v_pk_fma_f32 v[108:109], v[108:109], v[150:151], v[158:159]
	v_pk_fma_f32 v[110:111], v[110:111], v[152:153], v[160:161]
	v_pk_fma_f32 v[164:165], v[106:107], v[156:157], v[164:165]
	v_pk_fma_f32 v[106:107], v[104:105], v[154:155], v[162:163]
	v_cvt_pk_bf16_f32 v104, v108, v109
	v_cvt_pk_bf16_f32 v105, v110, v111
	v_cvt_pk_bf16_f32 v106, v106, v107
	v_cvt_pk_bf16_f32 v107, v164, v165
	global_store_dwordx4 v[242:243], v[104:107], off
	v_lshlrev_b32_e32 v150, 16, v194
	v_and_b32_e32 v151, 0xffff0000, v194
	v_lshlrev_b32_e32 v152, 16, v195
	v_and_b32_e32 v153, 0xffff0000, v195
	v_lshlrev_b32_e32 v154, 16, v196
	v_and_b32_e32 v155, 0xffff0000, v196
	v_lshlrev_b32_e32 v156, 16, v197
	v_and_b32_e32 v157, 0xffff0000, v197
	v_lshlrev_b32_e32 v158, 16, v222
	v_and_b32_e32 v159, 0xffff0000, v222
	v_lshlrev_b32_e32 v160, 16, v223
	v_and_b32_e32 v161, 0xffff0000, v223
	v_lshlrev_b32_e32 v162, 16, v224
	v_and_b32_e32 v163, 0xffff0000, v224
	v_lshlrev_b32_e32 v164, 16, v225
	v_and_b32_e32 v165, 0xffff0000, v225
	v_pk_fma_f32 v[100:101], v[100:101], v[150:151], v[158:159]
	v_pk_fma_f32 v[102:103], v[102:103], v[152:153], v[160:161]
	v_pk_fma_f32 v[164:165], v[98:99], v[156:157], v[164:165]
	v_pk_fma_f32 v[98:99], v[96:97], v[154:155], v[162:163]
	v_cvt_pk_bf16_f32 v96, v100, v101
	v_cvt_pk_bf16_f32 v97, v102, v103
	v_cvt_pk_bf16_f32 v98, v98, v99
	v_cvt_pk_bf16_f32 v99, v164, v165
	global_store_dwordx4 v[242:243], v[96:99], off offset:256
	s_nop 1
	v_add_u32_e32 v150, 0x80, v140
	v_ashrrev_i32_e32 v151, 31, v150
	v_lshlrev_b64 v[242:243], 12, v[150:151]
	v_mad_i64_i32 v[218:219], s[6:7], v150, s14, v[142:143]
	v_lshl_add_u64 v[242:243], s[90:91], 0, v[242:243]
	v_lshl_add_u64 v[218:219], v[218:219], 0, v[138:139]
	v_lshl_add_u64 v[242:243], v[242:243], 0, v[138:139]
	global_load_dwordx4 v[186:189], v[218:219], off
	global_load_dwordx4 v[190:193], v[242:243], off
	global_load_dwordx4 v[194:197], v[218:219], off offset:256
	global_load_dwordx4 v[222:225], v[242:243], off offset:256
	s_waitcnt vmcnt(12)
	v_lshlrev_b32_e32 v150, 16, v226
	v_and_b32_e32 v151, 0xffff0000, v226
	v_lshlrev_b32_e32 v152, 16, v227
	v_and_b32_e32 v153, 0xffff0000, v227
	v_lshlrev_b32_e32 v154, 16, v228
	v_and_b32_e32 v155, 0xffff0000, v228
	v_lshlrev_b32_e32 v156, 16, v229
	v_and_b32_e32 v157, 0xffff0000, v229
	v_lshlrev_b32_e32 v158, 16, v230
	v_and_b32_e32 v159, 0xffff0000, v230
	v_lshlrev_b32_e32 v160, 16, v231
	v_and_b32_e32 v161, 0xffff0000, v231
	v_lshlrev_b32_e32 v162, 16, v232
	v_and_b32_e32 v163, 0xffff0000, v232
	v_lshlrev_b32_e32 v164, 16, v233
	v_and_b32_e32 v165, 0xffff0000, v233
	v_pk_fma_f32 v[92:93], v[92:93], v[150:151], v[158:159]
	v_pk_fma_f32 v[94:95], v[94:95], v[152:153], v[160:161]
	v_pk_fma_f32 v[164:165], v[90:91], v[156:157], v[164:165]
	v_pk_fma_f32 v[90:91], v[88:89], v[154:155], v[162:163]
	v_cvt_pk_bf16_f32 v88, v92, v93
	v_cvt_pk_bf16_f32 v89, v94, v95
	v_cvt_pk_bf16_f32 v90, v90, v91
	v_cvt_pk_bf16_f32 v91, v164, v165
	global_store_dwordx4 v[246:247], v[88:91], off
	v_lshlrev_b32_e32 v150, 16, v234
	v_and_b32_e32 v151, 0xffff0000, v234
	v_lshlrev_b32_e32 v152, 16, v235
	v_and_b32_e32 v153, 0xffff0000, v235
	v_lshlrev_b32_e32 v154, 16, v236
	v_and_b32_e32 v155, 0xffff0000, v236
	v_lshlrev_b32_e32 v156, 16, v237
	v_and_b32_e32 v157, 0xffff0000, v237
	v_lshlrev_b32_e32 v158, 16, v238
	v_and_b32_e32 v159, 0xffff0000, v238
	v_lshlrev_b32_e32 v160, 16, v239
	v_and_b32_e32 v161, 0xffff0000, v239
	v_lshlrev_b32_e32 v162, 16, v240
	v_and_b32_e32 v163, 0xffff0000, v240
	v_lshlrev_b32_e32 v164, 16, v241
	v_and_b32_e32 v165, 0xffff0000, v241
	v_pk_fma_f32 v[84:85], v[84:85], v[150:151], v[158:159]
	v_pk_fma_f32 v[86:87], v[86:87], v[152:153], v[160:161]
	v_pk_fma_f32 v[164:165], v[82:83], v[156:157], v[164:165]
	v_pk_fma_f32 v[82:83], v[80:81], v[154:155], v[162:163]
	v_cvt_pk_bf16_f32 v80, v84, v85
	v_cvt_pk_bf16_f32 v81, v86, v87
	v_cvt_pk_bf16_f32 v82, v82, v83
	v_cvt_pk_bf16_f32 v83, v164, v165
	global_store_dwordx4 v[246:247], v[80:83], off offset:256
	s_nop 1
	v_add_u32_e32 v150, 0x90, v140
	v_ashrrev_i32_e32 v151, 31, v150
	v_lshlrev_b64 v[246:247], 12, v[150:151]
	v_mad_i64_i32 v[244:245], s[6:7], v150, s14, v[142:143]
	v_lshl_add_u64 v[246:247], s[90:91], 0, v[246:247]
	v_lshl_add_u64 v[244:245], v[244:245], 0, v[138:139]
	v_lshl_add_u64 v[246:247], v[246:247], 0, v[138:139]
	global_load_dwordx4 v[226:229], v[244:245], off
	global_load_dwordx4 v[230:233], v[246:247], off
	global_load_dwordx4 v[234:237], v[244:245], off offset:256
	global_load_dwordx4 v[238:241], v[246:247], off offset:256
	s_waitcnt vmcnt(12)
; DI float bflo(unsigned u) { return __uint_as_float(u << 16); }
; DI float bfhi(unsigned u) { return __uint_as_float(u & 0xffff0000u); }
; DI u32x4 pk8(const f32x4 a, const f32x4 b) { return (u32x4){pk2(a[0], a[1]), pk2(a[2], a[3]), pk2(b[0], b[1]), pk2(b[2], b[3])}; }
;     MI void operator()(const f32x4 (&acc)[2][2][4][2], const Unit& u, int wr, int wc, int fr, int fq) const {
;     ...
;                 const int row = u.pm * 256 + ai * 128 + wr * 64 + m * 16 + fr; const int col = u.pn * 256 + wc * 32 + 8 * fq;
;                 bf16_t* yp = Y + (size_t)row * DM + col; const bf16_t* gp = G + (size_t)row * RESTW + col;
; #pragma unroll
;                 for (int bj = 0; bj < 2; ++bj) {
;                     const u32x4 g = *(const u32x4*)(gp + bj * 128); const f32x4 a0 = acc[ai][bj][m][0], a1 = acc[ai][bj][m][1];
;                     f32x4 v0 = (f32x4){a0[0] * bflo(g.x), a0[1] * bfhi(g.x), a0[2] * bflo(g.y), a0[3] * bfhi(g.y)}, v1 = (f32x4){a1[0] * bflo(g.z), a1[1] * bfhi(g.z), a1[2] * bflo(g.w), a1[3] * bfhi(g.w)};
;                     if (!FIRST) { const u32x4 y = *(const u32x4*)(yp + bj * 128); v0 += (f32x4){bflo(y.x), bfhi(y.x), bflo(y.y), bfhi(y.y)}; v1 += (f32x4){bflo(y.z), bfhi(y.z), bflo(y.w), bfhi(y.w)}; }
;                     *(u32x4*)(yp + bj * 128) = pk8(v0, v1);
	v_lshlrev_b32_e32 v150, 16, v166
	v_and_b32_e32 v151, 0xffff0000, v166
	v_lshlrev_b32_e32 v152, 16, v167
	v_and_b32_e32 v153, 0xffff0000, v167
	v_lshlrev_b32_e32 v154, 16, v168
	v_and_b32_e32 v155, 0xffff0000, v168
	v_lshlrev_b32_e32 v156, 16, v169
	v_and_b32_e32 v157, 0xffff0000, v169
	v_lshlrev_b32_e32 v158, 16, v170
	v_and_b32_e32 v159, 0xffff0000, v170
	v_lshlrev_b32_e32 v160, 16, v171
	v_and_b32_e32 v161, 0xffff0000, v171
	v_lshlrev_b32_e32 v162, 16, v172
	v_and_b32_e32 v163, 0xffff0000, v172
	v_lshlrev_b32_e32 v164, 16, v173
	v_and_b32_e32 v165, 0xffff0000, v173
	v_pk_fma_f32 v[76:77], v[76:77], v[150:151], v[158:159]
	v_pk_fma_f32 v[78:79], v[78:79], v[152:153], v[160:161]
	v_pk_fma_f32 v[164:165], v[74:75], v[156:157], v[164:165]
	v_pk_fma_f32 v[74:75], v[72:73], v[154:155], v[162:163]
	v_cvt_pk_bf16_f32 v72, v76, v77
	v_cvt_pk_bf16_f32 v73, v78, v79
	v_cvt_pk_bf16_f32 v74, v74, v75
	v_cvt_pk_bf16_f32 v75, v164, v165
	global_store_dwordx4 v[250:251], v[72:75], off
	v_lshlrev_b32_e32 v150, 16, v174
	v_and_b32_e32 v151, 0xffff0000, v174
	v_lshlrev_b32_e32 v152, 16, v175
	v_and_b32_e32 v153, 0xffff0000, v175
	v_lshlrev_b32_e32 v154, 16, v176
	v_and_b32_e32 v155, 0xffff0000, v176
	v_lshlrev_b32_e32 v156, 16, v177
	v_and_b32_e32 v157, 0xffff0000, v177
	v_lshlrev_b32_e32 v158, 16, v178
	v_and_b32_e32 v159, 0xffff0000, v178
	v_lshlrev_b32_e32 v160, 16, v179
	v_and_b32_e32 v161, 0xffff0000, v179
	v_lshlrev_b32_e32 v162, 16, v180
	v_and_b32_e32 v163, 0xffff0000, v180
	v_lshlrev_b32_e32 v164, 16, v181
	v_and_b32_e32 v165, 0xffff0000, v181
	v_pk_fma_f32 v[68:69], v[68:69], v[150:151], v[158:159]
	v_pk_fma_f32 v[70:71], v[70:71], v[152:153], v[160:161]
	v_pk_fma_f32 v[164:165], v[66:67], v[156:157], v[164:165]
	v_pk_fma_f32 v[66:67], v[64:65], v[154:155], v[162:163]
	v_cvt_pk_bf16_f32 v64, v68, v69
	v_cvt_pk_bf16_f32 v65, v70, v71
	v_cvt_pk_bf16_f32 v66, v66, v67
	v_cvt_pk_bf16_f32 v67, v164, v165
	global_store_dwordx4 v[250:251], v[64:67], off offset:256
	s_nop 1
	v_add_u32_e32 v150, 0xa0, v140
	v_ashrrev_i32_e32 v151, 31, v150
	v_lshlrev_b64 v[250:251], 12, v[150:151]
	v_mad_i64_i32 v[182:183], s[6:7], v150, s14, v[142:143]
	v_lshl_add_u64 v[250:251], s[90:91], 0, v[250:251]
	v_lshl_add_u64 v[182:183], v[182:183], 0, v[138:139]
	v_lshl_add_u64 v[250:251], v[250:251], 0, v[138:139]
	global_load_dwordx4 v[166:169], v[182:183], off
	global_load_dwordx4 v[170:173], v[250:251], off
	global_load_dwordx4 v[174:177], v[182:183], off offset:256
	global_load_dwordx4 v[178:181], v[250:251], off offset:256
	s_waitcnt vmcnt(12)
	v_lshlrev_b32_e32 v150, 16, v186
	v_and_b32_e32 v151, 0xffff0000, v186
	v_lshlrev_b32_e32 v152, 16, v187
	v_and_b32_e32 v153, 0xffff0000, v187
	v_lshlrev_b32_e32 v154, 16, v188
	v_and_b32_e32 v155, 0xffff0000, v188
	v_lshlrev_b32_e32 v156, 16, v189
	v_and_b32_e32 v157, 0xffff0000, v189
	v_lshlrev_b32_e32 v158, 16, v190
	v_and_b32_e32 v159, 0xffff0000, v190
	v_lshlrev_b32_e32 v160, 16, v191
	v_and_b32_e32 v161, 0xffff0000, v191
	v_lshlrev_b32_e32 v162, 16, v192
	v_and_b32_e32 v163, 0xffff0000, v192
	v_lshlrev_b32_e32 v164, 16, v193
	v_and_b32_e32 v165, 0xffff0000, v193
	v_pk_fma_f32 v[60:61], v[60:61], v[150:151], v[158:159]
	v_pk_fma_f32 v[62:63], v[62:63], v[152:153], v[160:161]
	v_pk_fma_f32 v[164:165], v[58:59], v[156:157], v[164:165]
	v_pk_fma_f32 v[58:59], v[56:57], v[154:155], v[162:163]
	v_cvt_pk_bf16_f32 v56, v60, v61
	v_cvt_pk_bf16_f32 v57, v62, v63
	v_cvt_pk_bf16_f32 v58, v58, v59
	v_cvt_pk_bf16_f32 v59, v164, v165
	global_store_dwordx4 v[242:243], v[56:59], off
	v_lshlrev_b32_e32 v150, 16, v194
	v_and_b32_e32 v151, 0xffff0000, v194
	v_lshlrev_b32_e32 v152, 16, v195
	v_and_b32_e32 v153, 0xffff0000, v195
	v_lshlrev_b32_e32 v154, 16, v196
	v_and_b32_e32 v155, 0xffff0000, v196
	v_lshlrev_b32_e32 v156, 16, v197
	v_and_b32_e32 v157, 0xffff0000, v197
	v_lshlrev_b32_e32 v158, 16, v222
	v_and_b32_e32 v159, 0xffff0000, v222
	v_lshlrev_b32_e32 v160, 16, v223
	v_and_b32_e32 v161, 0xffff0000, v223
	v_lshlrev_b32_e32 v162, 16, v224
	v_and_b32_e32 v163, 0xffff0000, v224
	v_lshlrev_b32_e32 v164, 16, v225
	v_and_b32_e32 v165, 0xffff0000, v225
	v_pk_fma_f32 v[52:53], v[52:53], v[150:151], v[158:159]
	v_pk_fma_f32 v[54:55], v[54:55], v[152:153], v[160:161]
	v_pk_fma_f32 v[164:165], v[50:51], v[156:157], v[164:165]
	v_pk_fma_f32 v[50:51], v[48:49], v[154:155], v[162:163]
	v_cvt_pk_bf16_f32 v48, v52, v53
	v_cvt_pk_bf16_f32 v49, v54, v55
	v_cvt_pk_bf16_f32 v50, v50, v51
	v_cvt_pk_bf16_f32 v51, v164, v165
	global_store_dwordx4 v[242:243], v[48:51], off offset:256
	s_nop 1
	v_add_u32_e32 v150, 0xb0, v140
	v_ashrrev_i32_e32 v151, 31, v150
	v_lshlrev_b64 v[242:243], 12, v[150:151]
	v_mad_i64_i32 v[218:219], s[6:7], v150, s14, v[142:143]
	v_lshl_add_u64 v[242:243], s[90:91], 0, v[242:243]
	v_lshl_add_u64 v[218:219], v[218:219], 0, v[138:139]
	v_lshl_add_u64 v[242:243], v[242:243], 0, v[138:139]
	global_load_dwordx4 v[186:189], v[218:219], off
	global_load_dwordx4 v[190:193], v[242:243], off
	global_load_dwordx4 v[194:197], v[218:219], off offset:256
	global_load_dwordx4 v[222:225], v[242:243], off offset:256
	s_waitcnt vmcnt(12)
; DI float bflo(unsigned u) { return __uint_as_float(u << 16); }
; DI float bfhi(unsigned u) { return __uint_as_float(u & 0xffff0000u); }
; DI u32x4 pk8(const f32x4 a, const f32x4 b) { return (u32x4){pk2(a[0], a[1]), pk2(a[2], a[3]), pk2(b[0], b[1]), pk2(b[2], b[3])}; }
;     MI void operator()(const f32x4 (&acc)[2][2][4][2], const Unit& u, int wr, int wc, int fr, int fq) const {
;     ...
;         for (int ai = 0; ai < 2; ++ai)
; #pragma unroll
;             for (int m = 0; m < 4; ++m) {
;                 const int row = u.pm * 256 + ai * 128 + wr * 64 + m * 16 + fr; const int col = u.pn * 256 + wc * 32 + 8 * fq;
;                 bf16_t* yp = Y + (size_t)row * DM + col; const bf16_t* gp = G + (size_t)row * RESTW + col;
; #pragma unroll
;                 for (int bj = 0; bj < 2; ++bj) {
;                     const u32x4 g = *(const u32x4*)(gp + bj * 128); const f32x4 a0 = acc[ai][bj][m][0], a1 = acc[ai][bj][m][1];
;                     f32x4 v0 = (f32x4){a0[0] * bflo(g.x), a0[1] * bfhi(g.x), a0[2] * bflo(g.y), a0[3] * bfhi(g.y)}, v1 = (f32x4){a1[0] * bflo(g.z), a1[1] * bfhi(g.z), a1[2] * bflo(g.w), a1[3] * bfhi(g.w)};
;                     if (!FIRST) { const u32x4 y = *(const u32x4*)(yp + bj * 128); v0 += (f32x4){bflo(y.x), bfhi(y.x), bflo(y.y), bfhi(y.y)}; v1 += (f32x4){bflo(y.z), bfhi(y.z), bflo(y.w), bfhi(y.w)}; }
;                     *(u32x4*)(yp + bj * 128) = pk8(v0, v1);
;                 }
	v_lshlrev_b32_e32 v150, 16, v226
	v_and_b32_e32 v151, 0xffff0000, v226
	v_lshlrev_b32_e32 v152, 16, v227
	v_and_b32_e32 v153, 0xffff0000, v227
	v_lshlrev_b32_e32 v154, 16, v228
	v_and_b32_e32 v155, 0xffff0000, v228
	v_lshlrev_b32_e32 v156, 16, v229
	v_and_b32_e32 v157, 0xffff0000, v229
	v_lshlrev_b32_e32 v158, 16, v230
	v_and_b32_e32 v159, 0xffff0000, v230
	v_lshlrev_b32_e32 v160, 16, v231
	v_and_b32_e32 v161, 0xffff0000, v231
	v_lshlrev_b32_e32 v162, 16, v232
	v_and_b32_e32 v163, 0xffff0000, v232
	v_lshlrev_b32_e32 v164, 16, v233
	v_and_b32_e32 v165, 0xffff0000, v233
	v_pk_fma_f32 v[44:45], v[44:45], v[150:151], v[158:159]
	v_pk_fma_f32 v[46:47], v[46:47], v[152:153], v[160:161]
	v_pk_fma_f32 v[164:165], v[42:43], v[156:157], v[164:165]
	v_pk_fma_f32 v[42:43], v[40:41], v[154:155], v[162:163]
	v_cvt_pk_bf16_f32 v40, v44, v45
	v_cvt_pk_bf16_f32 v41, v46, v47
	v_cvt_pk_bf16_f32 v42, v42, v43
	v_cvt_pk_bf16_f32 v43, v164, v165
	global_store_dwordx4 v[246:247], v[40:43], off
	v_lshlrev_b32_e32 v150, 16, v234
	v_and_b32_e32 v151, 0xffff0000, v234
	v_lshlrev_b32_e32 v152, 16, v235
	v_and_b32_e32 v153, 0xffff0000, v235
	v_lshlrev_b32_e32 v154, 16, v236
	v_and_b32_e32 v155, 0xffff0000, v236
	v_lshlrev_b32_e32 v156, 16, v237
	v_and_b32_e32 v157, 0xffff0000, v237
	v_lshlrev_b32_e32 v158, 16, v238
	v_and_b32_e32 v159, 0xffff0000, v238
	v_lshlrev_b32_e32 v160, 16, v239
	v_and_b32_e32 v161, 0xffff0000, v239
	v_lshlrev_b32_e32 v162, 16, v240
	v_and_b32_e32 v163, 0xffff0000, v240
	v_lshlrev_b32_e32 v164, 16, v241
	v_and_b32_e32 v165, 0xffff0000, v241
	v_pk_fma_f32 v[36:37], v[36:37], v[150:151], v[158:159]
	v_pk_fma_f32 v[38:39], v[38:39], v[152:153], v[160:161]
	v_pk_fma_f32 v[164:165], v[34:35], v[156:157], v[164:165]
	v_pk_fma_f32 v[34:35], v[32:33], v[154:155], v[162:163]
	v_cvt_pk_bf16_f32 v32, v36, v37
	v_cvt_pk_bf16_f32 v33, v38, v39
	v_cvt_pk_bf16_f32 v34, v34, v35
	v_cvt_pk_bf16_f32 v35, v164, v165
	global_store_dwordx4 v[246:247], v[32:35], off offset:256
	s_waitcnt vmcnt(8)
	v_lshlrev_b32_e32 v150, 16, v166
	v_and_b32_e32 v151, 0xffff0000, v166
	v_lshlrev_b32_e32 v152, 16, v167
	v_and_b32_e32 v153, 0xffff0000, v167
	v_lshlrev_b32_e32 v154, 16, v168
	v_and_b32_e32 v155, 0xffff0000, v168
	v_lshlrev_b32_e32 v156, 16, v169
	v_and_b32_e32 v157, 0xffff0000, v169
	v_lshlrev_b32_e32 v158, 16, v170
	v_and_b32_e32 v159, 0xffff0000, v170
	v_lshlrev_b32_e32 v160, 16, v171
	v_and_b32_e32 v161, 0xffff0000, v171
	v_lshlrev_b32_e32 v162, 16, v172
	v_and_b32_e32 v163, 0xffff0000, v172
	v_lshlrev_b32_e32 v164, 16, v173
	v_and_b32_e32 v165, 0xffff0000, v173
	v_pk_fma_f32 v[28:29], v[28:29], v[150:151], v[158:159]
	v_pk_fma_f32 v[30:31], v[30:31], v[152:153], v[160:161]
	v_pk_fma_f32 v[164:165], v[26:27], v[156:157], v[164:165]
	v_pk_fma_f32 v[26:27], v[24:25], v[154:155], v[162:163]
	v_cvt_pk_bf16_f32 v24, v28, v29
	v_cvt_pk_bf16_f32 v25, v30, v31
	v_cvt_pk_bf16_f32 v26, v26, v27
	v_cvt_pk_bf16_f32 v27, v164, v165
	global_store_dwordx4 v[250:251], v[24:27], off
	v_lshlrev_b32_e32 v150, 16, v174
	v_and_b32_e32 v151, 0xffff0000, v174
	v_lshlrev_b32_e32 v152, 16, v175
	v_and_b32_e32 v153, 0xffff0000, v175
	v_lshlrev_b32_e32 v154, 16, v176
	v_and_b32_e32 v155, 0xffff0000, v176
	v_lshlrev_b32_e32 v156, 16, v177
	v_and_b32_e32 v157, 0xffff0000, v177
	v_lshlrev_b32_e32 v158, 16, v178
	v_and_b32_e32 v159, 0xffff0000, v178
	v_lshlrev_b32_e32 v160, 16, v179
	v_and_b32_e32 v161, 0xffff0000, v179
	v_lshlrev_b32_e32 v162, 16, v180
	v_and_b32_e32 v163, 0xffff0000, v180
	v_lshlrev_b32_e32 v164, 16, v181
	v_and_b32_e32 v165, 0xffff0000, v181
	v_pk_fma_f32 v[20:21], v[20:21], v[150:151], v[158:159]
	v_pk_fma_f32 v[22:23], v[22:23], v[152:153], v[160:161]
	v_pk_fma_f32 v[164:165], v[18:19], v[156:157], v[164:165]
	v_pk_fma_f32 v[18:19], v[16:17], v[154:155], v[162:163]
	v_cvt_pk_bf16_f32 v16, v20, v21
	v_cvt_pk_bf16_f32 v17, v22, v23
	v_cvt_pk_bf16_f32 v18, v18, v19
	v_cvt_pk_bf16_f32 v19, v164, v165
	global_store_dwordx4 v[250:251], v[16:19], off offset:256
	s_waitcnt vmcnt(4)
	v_lshlrev_b32_e32 v150, 16, v186
	v_and_b32_e32 v151, 0xffff0000, v186
	v_lshlrev_b32_e32 v152, 16, v187
	v_and_b32_e32 v153, 0xffff0000, v187
	v_lshlrev_b32_e32 v154, 16, v188
	v_and_b32_e32 v155, 0xffff0000, v188
	v_lshlrev_b32_e32 v156, 16, v189
	v_and_b32_e32 v157, 0xffff0000, v189
	v_lshlrev_b32_e32 v158, 16, v190
	v_and_b32_e32 v159, 0xffff0000, v190
	v_lshlrev_b32_e32 v160, 16, v191
	v_and_b32_e32 v161, 0xffff0000, v191
	v_lshlrev_b32_e32 v162, 16, v192
	v_and_b32_e32 v163, 0xffff0000, v192
	v_lshlrev_b32_e32 v164, 16, v193
	v_and_b32_e32 v165, 0xffff0000, v193
	v_pk_fma_f32 v[12:13], v[12:13], v[150:151], v[158:159]
	v_pk_fma_f32 v[14:15], v[14:15], v[152:153], v[160:161]
	v_pk_fma_f32 v[164:165], v[10:11], v[156:157], v[164:165]
	v_pk_fma_f32 v[10:11], v[8:9], v[154:155], v[162:163]
	v_cvt_pk_bf16_f32 v8, v12, v13
	v_cvt_pk_bf16_f32 v9, v14, v15
	v_cvt_pk_bf16_f32 v10, v10, v11
	v_cvt_pk_bf16_f32 v11, v164, v165
	global_store_dwordx4 v[242:243], v[8:11], off
	v_lshlrev_b32_e32 v150, 16, v194
	v_and_b32_e32 v151, 0xffff0000, v194
	v_lshlrev_b32_e32 v152, 16, v195
	v_and_b32_e32 v153, 0xffff0000, v195
	v_lshlrev_b32_e32 v154, 16, v196
	v_and_b32_e32 v155, 0xffff0000, v196
	v_lshlrev_b32_e32 v156, 16, v197
	v_and_b32_e32 v157, 0xffff0000, v197
	v_lshlrev_b32_e32 v158, 16, v222
	v_and_b32_e32 v159, 0xffff0000, v222
	v_lshlrev_b32_e32 v160, 16, v223
	v_and_b32_e32 v161, 0xffff0000, v223
	v_lshlrev_b32_e32 v162, 16, v224
	v_and_b32_e32 v163, 0xffff0000, v224
	v_lshlrev_b32_e32 v164, 16, v225
	v_and_b32_e32 v165, 0xffff0000, v225
	v_pk_fma_f32 v[4:5], v[4:5], v[150:151], v[158:159]
	v_pk_fma_f32 v[6:7], v[6:7], v[152:153], v[160:161]
	v_pk_fma_f32 v[164:165], v[2:3], v[156:157], v[164:165]
	v_pk_fma_f32 v[2:3], v[0:1], v[154:155], v[162:163]
	v_cvt_pk_bf16_f32 v0, v4, v5
	v_cvt_pk_bf16_f32 v1, v6, v7
	v_cvt_pk_bf16_f32 v2, v2, v3
	v_cvt_pk_bf16_f32 v3, v164, v165
	global_store_dwordx4 v[242:243], v[0:3], off offset:256
	s_cbranch_vccnz .LBB0_647
	s_andn2_b64 vcc, exec, s[8:9]
	s_cbranch_vccnz .LBB0_646
	s_barrier
	s_branch .LBB0_646

; DI float bflo(unsigned u) { return __uint_as_float(u << 16); }
; DI float bfhi(unsigned u) { return __uint_as_float(u & 0xffff0000u); }
; DI u32x4 pk8(const f32x4 a, const f32x4 b) { return (u32x4){pk2(a[0], a[1]), pk2(a[2], a[3]), pk2(b[0], b[1]), pk2(b[2], b[3])}; }
;     MI void operator()(const f32x4 (&acc)[2][2][4][2], const Unit& u, int wr, int wc, int fr, int fq) const {
;     ...
;         for (int ai = 0; ai < 2; ++ai)
; #pragma unroll
;             for (int m = 0; m < 4; ++m) {
;                 const int row = u.pm * 256 + ai * 128 + wr * 64 + m * 16 + fr; const int col = u.pn * 256 + wc * 32 + 8 * fq;
;                 bf16_t* yp = Y + (size_t)row * DM + col; const bf16_t* gp = G + (size_t)row * RESTW + col;
; #pragma unroll
;                 for (int bj = 0; bj < 2; ++bj) {
;                     const u32x4 g = *(const u32x4*)(gp + bj * 128); const f32x4 a0 = acc[ai][bj][m][0], a1 = acc[ai][bj][m][1];
;                     f32x4 v0 = (f32x4){a0[0] * bflo(g.x), a0[1] * bfhi(g.x), a0[2] * bflo(g.y), a0[3] * bfhi(g.y)}, v1 = (f32x4){a1[0] * bflo(g.z), a1[1] * bfhi(g.z), a1[2] * bflo(g.w), a1[3] * bfhi(g.w)};
;                     if (!FIRST) { const u32x4 y = *(const u32x4*)(yp + bj * 128); v0 += (f32x4){bflo(y.x), bfhi(y.x), bflo(y.y), bfhi(y.y)}; v1 += (f32x4){bflo(y.z), bfhi(y.z), bflo(y.w), bfhi(y.w)}; }
;                     *(u32x4*)(yp + bj * 128) = pk8(v0, v1);
;                 }
.LBB0_670:
	v_lshl_add_u32 v140, s80, 8, v146
	v_lshl_or_b32 v138, s78, 8, v148
	v_ashrrev_i32_e32 v141, 31, v140
	v_ashrrev_i32_e32 v139, 31, v138
	v_lshlrev_b64 v[142:143], 12, v[140:141]
	v_readlane_b32 s6, v254, 28
	v_lshl_add_u64 v[142:143], s[90:91], 0, v[142:143]
	v_lshlrev_b64 v[138:139], 1, v[138:139]
	v_readlane_b32 s7, v254, 29
	v_lshl_add_u64 v[144:145], v[142:143], 0, v[138:139]
	s_mov_b64 s[78:79], -1
	v_mov_b64_e32 v[142:143], s[6:7]
	v_mad_i64_i32 v[150:151], s[6:7], v140, s14, v[142:143]
	v_lshl_add_u64 v[154:155], v[150:151], 0, v[138:139]
	s_andn2_b64 vcc, exec, s[4:5]
	s_mov_b64 s[82:83], s[40:41]
	v_mov_b32_e32 v150, v140
	v_ashrrev_i32_e32 v151, 31, v150
	v_lshlrev_b64 v[250:251], 12, v[150:151]
	v_mad_i64_i32 v[182:183], s[6:7], v150, s14, v[142:143]
	v_lshl_add_u64 v[250:251], s[90:91], 0, v[250:251]
	v_lshl_add_u64 v[182:183], v[182:183], 0, v[138:139]
	v_lshl_add_u64 v[250:251], v[250:251], 0, v[138:139]
	global_load_dwordx4 v[166:169], v[182:183], off
	global_load_dwordx4 v[170:173], v[250:251], off
	global_load_dwordx4 v[174:177], v[182:183], off offset:256
	global_load_dwordx4 v[178:181], v[250:251], off offset:256
	v_add_u32_e32 v150, 0x10, v140
	v_ashrrev_i32_e32 v151, 31, v150
	v_lshlrev_b64 v[242:243], 12, v[150:151]
	v_mad_i64_i32 v[218:219], s[6:7], v150, s14, v[142:143]
	v_lshl_add_u64 v[242:243], s[90:91], 0, v[242:243]
	v_lshl_add_u64 v[218:219], v[218:219], 0, v[138:139]
	v_lshl_add_u64 v[242:243], v[242:243], 0, v[138:139]
	global_load_dwordx4 v[186:189], v[218:219], off
	global_load_dwordx4 v[190:193], v[242:243], off
	global_load_dwordx4 v[194:197], v[218:219], off offset:256
	global_load_dwordx4 v[222:225], v[242:243], off offset:256
	v_add_u32_e32 v150, 0x20, v140
	v_ashrrev_i32_e32 v151, 31, v150
	v_lshlrev_b64 v[246:247], 12, v[150:151]
	v_mad_i64_i32 v[244:245], s[6:7], v150, s14, v[142:143]
	v_lshl_add_u64 v[246:247], s[90:91], 0, v[246:247]
	v_lshl_add_u64 v[244:245], v[244:245], 0, v[138:139]
	v_lshl_add_u64 v[246:247], v[246:247], 0, v[138:139]
	global_load_dwordx4 v[226:229], v[244:245], off
	global_load_dwordx4 v[230:233], v[246:247], off
	global_load_dwordx4 v[234:237], v[244:245], off offset:256
	global_load_dwordx4 v[238:241], v[246:247], off offset:256
	s_waitcnt vmcnt(8)
	v_lshlrev_b32_e32 v150, 16, v166
	v_and_b32_e32 v151, 0xffff0000, v166
	v_lshlrev_b32_e32 v152, 16, v167
	v_and_b32_e32 v153, 0xffff0000, v167
	v_lshlrev_b32_e32 v154, 16, v168
	v_and_b32_e32 v155, 0xffff0000, v168
	v_lshlrev_b32_e32 v156, 16, v169
	v_and_b32_e32 v157, 0xffff0000, v169
	v_lshlrev_b32_e32 v158, 16, v170
	v_and_b32_e32 v159, 0xffff0000, v170
	v_lshlrev_b32_e32 v160, 16, v171
	v_and_b32_e32 v161, 0xffff0000, v171
	v_lshlrev_b32_e32 v162, 16, v172
	v_and_b32_e32 v163, 0xffff0000, v172
	v_lshlrev_b32_e32 v164, 16, v173
	v_and_b32_e32 v165, 0xffff0000, v173
	v_pk_fma_f32 v[124:125], v[124:125], v[150:151], v[158:159]
	v_pk_fma_f32 v[126:127], v[126:127], v[152:153], v[160:161]
	v_pk_fma_f32 v[164:165], v[122:123], v[156:157], v[164:165]
	v_pk_fma_f32 v[122:123], v[120:121], v[154:155], v[162:163]
	v_cvt_pk_bf16_f32 v120, v124, v125
	v_cvt_pk_bf16_f32 v121, v126, v127
	v_cvt_pk_bf16_f32 v122, v122, v123
	v_cvt_pk_bf16_f32 v123, v164, v165
	global_store_dwordx4 v[250:251], v[120:123], off
	v_lshlrev_b32_e32 v150, 16, v174
	v_and_b32_e32 v151, 0xffff0000, v174
	v_lshlrev_b32_e32 v152, 16, v175
	v_and_b32_e32 v153, 0xffff0000, v175
	v_lshlrev_b32_e32 v154, 16, v176
	v_and_b32_e32 v155, 0xffff0000, v176
	v_lshlrev_b32_e32 v156, 16, v177
	v_and_b32_e32 v157, 0xffff0000, v177
	v_lshlrev_b32_e32 v158, 16, v178
	v_and_b32_e32 v159, 0xffff0000, v178
	v_lshlrev_b32_e32 v160, 16, v179
	v_and_b32_e32 v161, 0xffff0000, v179
	v_lshlrev_b32_e32 v162, 16, v180
	v_and_b32_e32 v163, 0xffff0000, v180
	v_lshlrev_b32_e32 v164, 16, v181
	v_and_b32_e32 v165, 0xffff0000, v181
	v_pk_fma_f32 v[116:117], v[116:117], v[150:151], v[158:159]
	v_pk_fma_f32 v[118:119], v[118:119], v[152:153], v[160:161]
	v_pk_fma_f32 v[164:165], v[114:115], v[156:157], v[164:165]
	v_pk_fma_f32 v[114:115], v[112:113], v[154:155], v[162:163]
	v_cvt_pk_bf16_f32 v112, v116, v117
	v_cvt_pk_bf16_f32 v113, v118, v119
	v_cvt_pk_bf16_f32 v114, v114, v115
	v_cvt_pk_bf16_f32 v115, v164, v165
	global_store_dwordx4 v[250:251], v[112:115], off offset:256
	s_nop 1
	v_add_u32_e32 v150, 0x30, v140
	v_ashrrev_i32_e32 v151, 31, v150
	v_lshlrev_b64 v[250:251], 12, v[150:151]
	v_mad_i64_i32 v[182:183], s[6:7], v150, s14, v[142:143]
	v_lshl_add_u64 v[250:251], s[90:91], 0, v[250:251]
	v_lshl_add_u64 v[182:183], v[182:183], 0, v[138:139]
	v_lshl_add_u64 v[250:251], v[250:251], 0, v[138:139]
	global_load_dwordx4 v[166:169], v[182:183], off
	global_load_dwordx4 v[170:173], v[250:251], off
	global_load_dwordx4 v[174:177], v[182:183], off offset:256
	global_load_dwordx4 v[178:181], v[250:251], off offset:256
	s_waitcnt vmcnt(10)
; DI float bflo(unsigned u) { return __uint_as_float(u << 16); }
; DI float bfhi(unsigned u) { return __uint_as_float(u & 0xffff0000u); }
; DI u32x4 pk8(const f32x4 a, const f32x4 b) { return (u32x4){pk2(a[0], a[1]), pk2(a[2], a[3]), pk2(b[0], b[1]), pk2(b[2], b[3])}; }
;     MI void operator()(const f32x4 (&acc)[2][2][4][2], const Unit& u, int wr, int wc, int fr, int fq) const {
;     ...
;         for (int ai = 0; ai < 2; ++ai)
; #pragma unroll
;             for (int m = 0; m < 4; ++m) {
;                 const int row = u.pm * 256 + ai * 128 + wr * 64 + m * 16 + fr; const int col = u.pn * 256 + wc * 32 + 8 * fq;
;                 bf16_t* yp = Y + (size_t)row * DM + col; const bf16_t* gp = G + (size_t)row * RESTW + col;
; #pragma unroll
;                 for (int bj = 0; bj < 2; ++bj) {
;                     const u32x4 g = *(const u32x4*)(gp + bj * 128); const f32x4 a0 = acc[ai][bj][m][0], a1 = acc[ai][bj][m][1];
;                     f32x4 v0 = (f32x4){a0[0] * bflo(g.x), a0[1] * bfhi(g.x), a0[2] * bflo(g.y), a0[3] * bfhi(g.y)}, v1 = (f32x4){a1[0] * bflo(g.z), a1[1] * bfhi(g.z), a1[2] * bflo(g.w), a1[3] * bfhi(g.w)};
;                     if (!FIRST) { const u32x4 y = *(const u32x4*)(yp + bj * 128); v0 += (f32x4){bflo(y.x), bfhi(y.x), bflo(y.y), bfhi(y.y)}; v1 += (f32x4){bflo(y.z), bfhi(y.z), bflo(y.w), bfhi(y.w)}; }
;                     *(u32x4*)(yp + bj * 128) = pk8(v0, v1);
;                 }
	v_lshlrev_b32_e32 v150, 16, v186
	v_and_b32_e32 v151, 0xffff0000, v186
	v_lshlrev_b32_e32 v152, 16, v187
	v_and_b32_e32 v153, 0xffff0000, v187
	v_lshlrev_b32_e32 v154, 16, v188
	v_and_b32_e32 v155, 0xffff0000, v188
	v_lshlrev_b32_e32 v156, 16, v189
	v_and_b32_e32 v157, 0xffff0000, v189
	v_lshlrev_b32_e32 v158, 16, v190
	v_and_b32_e32 v159, 0xffff0000, v190
	v_lshlrev_b32_e32 v160, 16, v191
	v_and_b32_e32 v161, 0xffff0000, v191
	v_lshlrev_b32_e32 v162, 16, v192
	v_and_b32_e32 v163, 0xffff0000, v192
	v_lshlrev_b32_e32 v164, 16, v193
	v_and_b32_e32 v165, 0xffff0000, v193
	v_pk_fma_f32 v[108:109], v[108:109], v[150:151], v[158:159]
	v_pk_fma_f32 v[110:111], v[110:111], v[152:153], v[160:161]
	v_pk_fma_f32 v[164:165], v[106:107], v[156:157], v[164:165]
	v_pk_fma_f32 v[106:107], v[104:105], v[154:155], v[162:163]
	v_cvt_pk_bf16_f32 v104, v108, v109
	v_cvt_pk_bf16_f32 v105, v110, v111
	v_cvt_pk_bf16_f32 v106, v106, v107
	v_cvt_pk_bf16_f32 v107, v164, v165
	global_store_dwordx4 v[242:243], v[104:107], off
	v_lshlrev_b32_e32 v150, 16, v194
	v_and_b32_e32 v151, 0xffff0000, v194
	v_lshlrev_b32_e32 v152, 16, v195
	v_and_b32_e32 v153, 0xffff0000, v195
	v_lshlrev_b32_e32 v154, 16, v196
	v_and_b32_e32 v155, 0xffff0000, v196
	v_lshlrev_b32_e32 v156, 16, v197
	v_and_b32_e32 v157, 0xffff0000, v197
	v_lshlrev_b32_e32 v158, 16, v222
	v_and_b32_e32 v159, 0xffff0000, v222
	v_lshlrev_b32_e32 v160, 16, v223
	v_and_b32_e32 v161, 0xffff0000, v223
	v_lshlrev_b32_e32 v162, 16, v224
	v_and_b32_e32 v163, 0xffff0000, v224
	v_lshlrev_b32_e32 v164, 16, v225
	v_and_b32_e32 v165, 0xffff0000, v225
	v_pk_fma_f32 v[100:101], v[100:101], v[150:151], v[158:159]
	v_pk_fma_f32 v[102:103], v[102:103], v[152:153], v[160:161]
	v_pk_fma_f32 v[164:165], v[98:99], v[156:157], v[164:165]
	v_pk_fma_f32 v[98:99], v[96:97], v[154:155], v[162:163]
	v_cvt_pk_bf16_f32 v96, v100, v101
	v_cvt_pk_bf16_f32 v97, v102, v103
	v_cvt_pk_bf16_f32 v98, v98, v99
	v_cvt_pk_bf16_f32 v99, v164, v165
	global_store_dwordx4 v[242:243], v[96:99], off offset:256
	s_nop 1
	v_add_u32_e32 v150, 0x80, v140
	v_ashrrev_i32_e32 v151, 31, v150
	v_lshlrev_b64 v[242:243], 12, v[150:151]
	v_mad_i64_i32 v[218:219], s[6:7], v150, s14, v[142:143]
	v_lshl_add_u64 v[242:243], s[90:91], 0, v[242:243]
	v_lshl_add_u64 v[218:219], v[218:219], 0, v[138:139]
	v_lshl_add_u64 v[242:243], v[242:243], 0, v[138:139]
	global_load_dwordx4 v[186:189], v[218:219], off
	global_load_dwordx4 v[190:193], v[242:243], off
	global_load_dwordx4 v[194:197], v[218:219], off offset:256
	global_load_dwordx4 v[222:225], v[242:243], off offset:256
	s_waitcnt vmcnt(12)
	v_lshlrev_b32_e32 v150, 16, v226
	v_and_b32_e32 v151, 0xffff0000, v226
	v_lshlrev_b32_e32 v152, 16, v227
	v_and_b32_e32 v153, 0xffff0000, v227
	v_lshlrev_b32_e32 v154, 16, v228
	v_and_b32_e32 v155, 0xffff0000, v228
	v_lshlrev_b32_e32 v156, 16, v229
	v_and_b32_e32 v157, 0xffff0000, v229
	v_lshlrev_b32_e32 v158, 16, v230
	v_and_b32_e32 v159, 0xffff0000, v230
	v_lshlrev_b32_e32 v160, 16, v231
	v_and_b32_e32 v161, 0xffff0000, v231
	v_lshlrev_b32_e32 v162, 16, v232
	v_and_b32_e32 v163, 0xffff0000, v232
	v_lshlrev_b32_e32 v164, 16, v233
	v_and_b32_e32 v165, 0xffff0000, v233
	v_pk_fma_f32 v[92:93], v[92:93], v[150:151], v[158:159]
	v_pk_fma_f32 v[94:95], v[94:95], v[152:153], v[160:161]
	v_pk_fma_f32 v[164:165], v[90:91], v[156:157], v[164:165]
	v_pk_fma_f32 v[90:91], v[88:89], v[154:155], v[162:163]
	v_cvt_pk_bf16_f32 v88, v92, v93
	v_cvt_pk_bf16_f32 v89, v94, v95
	v_cvt_pk_bf16_f32 v90, v90, v91
	v_cvt_pk_bf16_f32 v91, v164, v165
	global_store_dwordx4 v[246:247], v[88:91], off
	v_lshlrev_b32_e32 v150, 16, v234
	v_and_b32_e32 v151, 0xffff0000, v234
	v_lshlrev_b32_e32 v152, 16, v235
	v_and_b32_e32 v153, 0xffff0000, v235
	v_lshlrev_b32_e32 v154, 16, v236
	v_and_b32_e32 v155, 0xffff0000, v236
	v_lshlrev_b32_e32 v156, 16, v237
	v_and_b32_e32 v157, 0xffff0000, v237
	v_lshlrev_b32_e32 v158, 16, v238
	v_and_b32_e32 v159, 0xffff0000, v238
	v_lshlrev_b32_e32 v160, 16, v239
	v_and_b32_e32 v161, 0xffff0000, v239
	v_lshlrev_b32_e32 v162, 16, v240
	v_and_b32_e32 v163, 0xffff0000, v240
	v_lshlrev_b32_e32 v164, 16, v241
	v_and_b32_e32 v165, 0xffff0000, v241
	v_pk_fma_f32 v[84:85], v[84:85], v[150:151], v[158:159]
	v_pk_fma_f32 v[86:87], v[86:87], v[152:153], v[160:161]
	v_pk_fma_f32 v[164:165], v[82:83], v[156:157], v[164:165]
	v_pk_fma_f32 v[82:83], v[80:81], v[154:155], v[162:163]
	v_cvt_pk_bf16_f32 v80, v84, v85
	v_cvt_pk_bf16_f32 v81, v86, v87
	v_cvt_pk_bf16_f32 v82, v82, v83
	v_cvt_pk_bf16_f32 v83, v164, v165
	global_store_dwordx4 v[246:247], v[80:83], off offset:256
	s_nop 1
	v_add_u32_e32 v150, 0x90, v140
	v_ashrrev_i32_e32 v151, 31, v150
	v_lshlrev_b64 v[246:247], 12, v[150:151]
	v_mad_i64_i32 v[244:245], s[6:7], v150, s14, v[142:143]
	v_lshl_add_u64 v[246:247], s[90:91], 0, v[246:247]
	v_lshl_add_u64 v[244:245], v[244:245], 0, v[138:139]
	v_lshl_add_u64 v[246:247], v[246:247], 0, v[138:139]
	global_load_dwordx4 v[226:229], v[244:245], off
	global_load_dwordx4 v[230:233], v[246:247], off
	global_load_dwordx4 v[234:237], v[244:245], off offset:256
	global_load_dwordx4 v[238:241], v[246:247], off offset:256
	s_waitcnt vmcnt(12)
; DI float bflo(unsigned u) { return __uint_as_float(u << 16); }
; DI float bfhi(unsigned u) { return __uint_as_float(u & 0xffff0000u); }
; DI u32x4 pk8(const f32x4 a, const f32x4 b) { return (u32x4){pk2(a[0], a[1]), pk2(a[2], a[3]), pk2(b[0], b[1]), pk2(b[2], b[3])}; }
;     MI void operator()(const f32x4 (&acc)[2][2][4][2], const Unit& u, int wr, int wc, int fr, int fq) const {
;     ...
;         for (int ai = 0; ai < 2; ++ai)
; #pragma unroll
;             for (int m = 0; m < 4; ++m) {
;                 const int row = u.pm * 256 + ai * 128 + wr * 64 + m * 16 + fr; const int col = u.pn * 256 + wc * 32 + 8 * fq;
;                 bf16_t* yp = Y + (size_t)row * DM + col; const bf16_t* gp = G + (size_t)row * RESTW + col;
; #pragma unroll
;                 for (int bj = 0; bj < 2; ++bj) {
;                     const u32x4 g = *(const u32x4*)(gp + bj * 128); const f32x4 a0 = acc[ai][bj][m][0], a1 = acc[ai][bj][m][1];
;                     f32x4 v0 = (f32x4){a0[0] * bflo(g.x), a0[1] * bfhi(g.x), a0[2] * bflo(g.y), a0[3] * bfhi(g.y)}, v1 = (f32x4){a1[0] * bflo(g.z), a1[1] * bfhi(g.z), a1[2] * bflo(g.w), a1[3] * bfhi(g.w)};
;                     if (!FIRST) { const u32x4 y = *(const u32x4*)(yp + bj * 128); v0 += (f32x4){bflo(y.x), bfhi(y.x), bflo(y.y), bfhi(y.y)}; v1 += (f32x4){bflo(y.z), bfhi(y.z), bflo(y.w), bfhi(y.w)}; }
;                     *(u32x4*)(yp + bj * 128) = pk8(v0, v1);
;                 }
	v_lshlrev_b32_e32 v150, 16, v166
	v_and_b32_e32 v151, 0xffff0000, v166
	v_lshlrev_b32_e32 v152, 16, v167
	v_and_b32_e32 v153, 0xffff0000, v167
	v_lshlrev_b32_e32 v154, 16, v168
	v_and_b32_e32 v155, 0xffff0000, v168
	v_lshlrev_b32_e32 v156, 16, v169
	v_and_b32_e32 v157, 0xffff0000, v169
	v_lshlrev_b32_e32 v158, 16, v170
	v_and_b32_e32 v159, 0xffff0000, v170
	v_lshlrev_b32_e32 v160, 16, v171
	v_and_b32_e32 v161, 0xffff0000, v171
	v_lshlrev_b32_e32 v162, 16, v172
	v_and_b32_e32 v163, 0xffff0000, v172
	v_lshlrev_b32_e32 v164, 16, v173
	v_and_b32_e32 v165, 0xffff0000, v173
	v_pk_fma_f32 v[76:77], v[76:77], v[150:151], v[158:159]
	v_pk_fma_f32 v[78:79], v[78:79], v[152:153], v[160:161]
	v_pk_fma_f32 v[164:165], v[74:75], v[156:157], v[164:165]
	v_pk_fma_f32 v[74:75], v[72:73], v[154:155], v[162:163]
	v_cvt_pk_bf16_f32 v72, v76, v77
	v_cvt_pk_bf16_f32 v73, v78, v79
	v_cvt_pk_bf16_f32 v74, v74, v75
	v_cvt_pk_bf16_f32 v75, v164, v165
	global_store_dwordx4 v[250:251], v[72:75], off
	v_lshlrev_b32_e32 v150, 16, v174
	v_and_b32_e32 v151, 0xffff0000, v174
	v_lshlrev_b32_e32 v152, 16, v175
	v_and_b32_e32 v153, 0xffff0000, v175
	v_lshlrev_b32_e32 v154, 16, v176
	v_and_b32_e32 v155, 0xffff0000, v176
	v_lshlrev_b32_e32 v156, 16, v177
	v_and_b32_e32 v157, 0xffff0000, v177
	v_lshlrev_b32_e32 v158, 16, v178
	v_and_b32_e32 v159, 0xffff0000, v178
	v_lshlrev_b32_e32 v160, 16, v179
	v_and_b32_e32 v161, 0xffff0000, v179
	v_lshlrev_b32_e32 v162, 16, v180
	v_and_b32_e32 v163, 0xffff0000, v180
	v_lshlrev_b32_e32 v164, 16, v181
	v_and_b32_e32 v165, 0xffff0000, v181
	v_pk_fma_f32 v[68:69], v[68:69], v[150:151], v[158:159]
	v_pk_fma_f32 v[70:71], v[70:71], v[152:153], v[160:161]
	v_pk_fma_f32 v[164:165], v[66:67], v[156:157], v[164:165]
	v_pk_fma_f32 v[66:67], v[64:65], v[154:155], v[162:163]
	v_cvt_pk_bf16_f32 v64, v68, v69
	v_cvt_pk_bf16_f32 v65, v70, v71
	v_cvt_pk_bf16_f32 v66, v66, v67
	v_cvt_pk_bf16_f32 v67, v164, v165
	global_store_dwordx4 v[250:251], v[64:67], off offset:256
	s_nop 1
	v_add_u32_e32 v150, 0xa0, v140
	v_ashrrev_i32_e32 v151, 31, v150
	v_lshlrev_b64 v[250:251], 12, v[150:151]
	v_mad_i64_i32 v[182:183], s[6:7], v150, s14, v[142:143]
	v_lshl_add_u64 v[250:251], s[90:91], 0, v[250:251]
	v_lshl_add_u64 v[182:183], v[182:183], 0, v[138:139]
	v_lshl_add_u64 v[250:251], v[250:251], 0, v[138:139]
	global_load_dwordx4 v[166:169], v[182:183], off
	global_load_dwordx4 v[170:173], v[250:251], off
	global_load_dwordx4 v[174:177], v[182:183], off offset:256
	global_load_dwordx4 v[178:181], v[250:251], off offset:256
	s_waitcnt vmcnt(12)
	v_lshlrev_b32_e32 v150, 16, v186
	v_and_b32_e32 v151, 0xffff0000, v186
	v_lshlrev_b32_e32 v152, 16, v187
	v_and_b32_e32 v153, 0xffff0000, v187
	v_lshlrev_b32_e32 v154, 16, v188
	v_and_b32_e32 v155, 0xffff0000, v188
	v_lshlrev_b32_e32 v156, 16, v189
	v_and_b32_e32 v157, 0xffff0000, v189
	v_lshlrev_b32_e32 v158, 16, v190
	v_and_b32_e32 v159, 0xffff0000, v190
	v_lshlrev_b32_e32 v160, 16, v191
	v_and_b32_e32 v161, 0xffff0000, v191
	v_lshlrev_b32_e32 v162, 16, v192
	v_and_b32_e32 v163, 0xffff0000, v192
	v_lshlrev_b32_e32 v164, 16, v193
	v_and_b32_e32 v165, 0xffff0000, v193
	v_pk_fma_f32 v[60:61], v[60:61], v[150:151], v[158:159]
	v_pk_fma_f32 v[62:63], v[62:63], v[152:153], v[160:161]
	v_pk_fma_f32 v[164:165], v[58:59], v[156:157], v[164:165]
	v_pk_fma_f32 v[58:59], v[56:57], v[154:155], v[162:163]
	v_cvt_pk_bf16_f32 v56, v60, v61
	v_cvt_pk_bf16_f32 v57, v62, v63
	v_cvt_pk_bf16_f32 v58, v58, v59
	v_cvt_pk_bf16_f32 v59, v164, v165
	global_store_dwordx4 v[242:243], v[56:59], off
	v_lshlrev_b32_e32 v150, 16, v194
	v_and_b32_e32 v151, 0xffff0000, v194
	v_lshlrev_b32_e32 v152, 16, v195
	v_and_b32_e32 v153, 0xffff0000, v195
	v_lshlrev_b32_e32 v154, 16, v196
	v_and_b32_e32 v155, 0xffff0000, v196
	v_lshlrev_b32_e32 v156, 16, v197
	v_and_b32_e32 v157, 0xffff0000, v197
	v_lshlrev_b32_e32 v158, 16, v222
	v_and_b32_e32 v159, 0xffff0000, v222
	v_lshlrev_b32_e32 v160, 16, v223
	v_and_b32_e32 v161, 0xffff0000, v223
	v_lshlrev_b32_e32 v162, 16, v224
	v_and_b32_e32 v163, 0xffff0000, v224
	v_lshlrev_b32_e32 v164, 16, v225
	v_and_b32_e32 v165, 0xffff0000, v225
	v_pk_fma_f32 v[52:53], v[52:53], v[150:151], v[158:159]
	v_pk_fma_f32 v[54:55], v[54:55], v[152:153], v[160:161]
	v_pk_fma_f32 v[164:165], v[50:51], v[156:157], v[164:165]
	v_pk_fma_f32 v[50:51], v[48:49], v[154:155], v[162:163]
	v_cvt_pk_bf16_f32 v48, v52, v53
	v_cvt_pk_bf16_f32 v49, v54, v55
	v_cvt_pk_bf16_f32 v50, v50, v51
	v_cvt_pk_bf16_f32 v51, v164, v165
	global_store_dwordx4 v[242:243], v[48:51], off offset:256
	s_nop 1
	v_add_u32_e32 v150, 0xb0, v140
	v_ashrrev_i32_e32 v151, 31, v150
	v_lshlrev_b64 v[242:243], 12, v[150:151]
	v_mad_i64_i32 v[218:219], s[6:7], v150, s14, v[142:143]
	v_lshl_add_u64 v[242:243], s[90:91], 0, v[242:243]
	v_lshl_add_u64 v[218:219], v[218:219], 0, v[138:139]
	v_lshl_add_u64 v[242:243], v[242:243], 0, v[138:139]
	global_load_dwordx4 v[186:189], v[218:219], off
	global_load_dwordx4 v[190:193], v[242:243], off
	global_load_dwordx4 v[194:197], v[218:219], off offset:256
	global_load_dwordx4 v[222:225], v[242:243], off offset:256
	s_waitcnt vmcnt(12)
; DI float bflo(unsigned u) { return __uint_as_float(u << 16); }
; DI float bfhi(unsigned u) { return __uint_as_float(u & 0xffff0000u); }
; DI u32x4 pk8(const f32x4 a, const f32x4 b) { return (u32x4){pk2(a[0], a[1]), pk2(a[2], a[3]), pk2(b[0], b[1]), pk2(b[2], b[3])}; }
;     MI void operator()(const f32x4 (&acc)[2][2][4][2], const Unit& u, int wr, int wc, int fr, int fq) const {
;     ...
;         for (int ai = 0; ai < 2; ++ai)
; #pragma unroll
;             for (int m = 0; m < 4; ++m) {
;                 const int row = u.pm * 256 + ai * 128 + wr * 64 + m * 16 + fr; const int col = u.pn * 256 + wc * 32 + 8 * fq;
;                 bf16_t* yp = Y + (size_t)row * DM + col; const bf16_t* gp = G + (size_t)row * RESTW + col;
; #pragma unroll
;                 for (int bj = 0; bj < 2; ++bj) {
;                     const u32x4 g = *(const u32x4*)(gp + bj * 128); const f32x4 a0 = acc[ai][bj][m][0], a1 = acc[ai][bj][m][1];
;                     f32x4 v0 = (f32x4){a0[0] * bflo(g.x), a0[1] * bfhi(g.x), a0[2] * bflo(g.y), a0[3] * bfhi(g.y)}, v1 = (f32x4){a1[0] * bflo(g.z), a1[1] * bfhi(g.z), a1[2] * bflo(g.w), a1[3] * bfhi(g.w)};
;                     if (!FIRST) { const u32x4 y = *(const u32x4*)(yp + bj * 128); v0 += (f32x4){bflo(y.x), bfhi(y.x), bflo(y.y), bfhi(y.y)}; v1 += (f32x4){bflo(y.z), bfhi(y.z), bflo(y.w), bfhi(y.w)}; }
;                     *(u32x4*)(yp + bj * 128) = pk8(v0, v1);
;                 }
	v_lshlrev_b32_e32 v150, 16, v226
	v_and_b32_e32 v151, 0xffff0000, v226
	v_lshlrev_b32_e32 v152, 16, v227
	v_and_b32_e32 v153, 0xffff0000, v227
	v_lshlrev_b32_e32 v154, 16, v228
	v_and_b32_e32 v155, 0xffff0000, v228
	v_lshlrev_b32_e32 v156, 16, v229
	v_and_b32_e32 v157, 0xffff0000, v229
	v_lshlrev_b32_e32 v158, 16, v230
	v_and_b32_e32 v159, 0xffff0000, v230
	v_lshlrev_b32_e32 v160, 16, v231
	v_and_b32_e32 v161, 0xffff0000, v231
	v_lshlrev_b32_e32 v162, 16, v232
	v_and_b32_e32 v163, 0xffff0000, v232
	v_lshlrev_b32_e32 v164, 16, v233
	v_and_b32_e32 v165, 0xffff0000, v233
	v_pk_fma_f32 v[44:45], v[44:45], v[150:151], v[158:159]
	v_pk_fma_f32 v[46:47], v[46:47], v[152:153], v[160:161]
	v_pk_fma_f32 v[164:165], v[42:43], v[156:157], v[164:165]
	v_pk_fma_f32 v[42:43], v[40:41], v[154:155], v[162:163]
	v_cvt_pk_bf16_f32 v40, v44, v45
	v_cvt_pk_bf16_f32 v41, v46, v47
	v_cvt_pk_bf16_f32 v42, v42, v43
	v_cvt_pk_bf16_f32 v43, v164, v165
	global_store_dwordx4 v[246:247], v[40:43], off
	v_lshlrev_b32_e32 v150, 16, v234
	v_and_b32_e32 v151, 0xffff0000, v234
	v_lshlrev_b32_e32 v152, 16, v235
	v_and_b32_e32 v153, 0xffff0000, v235
	v_lshlrev_b32_e32 v154, 16, v236
	v_and_b32_e32 v155, 0xffff0000, v236
	v_lshlrev_b32_e32 v156, 16, v237
	v_and_b32_e32 v157, 0xffff0000, v237
	v_lshlrev_b32_e32 v158, 16, v238
	v_and_b32_e32 v159, 0xffff0000, v238
	v_lshlrev_b32_e32 v160, 16, v239
	v_and_b32_e32 v161, 0xffff0000, v239
	v_lshlrev_b32_e32 v162, 16, v240
	v_and_b32_e32 v163, 0xffff0000, v240
	v_lshlrev_b32_e32 v164, 16, v241
	v_and_b32_e32 v165, 0xffff0000, v241
	v_pk_fma_f32 v[36:37], v[36:37], v[150:151], v[158:159]
	v_pk_fma_f32 v[38:39], v[38:39], v[152:153], v[160:161]
	v_pk_fma_f32 v[164:165], v[34:35], v[156:157], v[164:165]
	v_pk_fma_f32 v[34:35], v[32:33], v[154:155], v[162:163]
	v_cvt_pk_bf16_f32 v32, v36, v37
	v_cvt_pk_bf16_f32 v33, v38, v39
	v_cvt_pk_bf16_f32 v34, v34, v35
	v_cvt_pk_bf16_f32 v35, v164, v165
	global_store_dwordx4 v[246:247], v[32:35], off offset:256
	s_waitcnt vmcnt(8)
	v_lshlrev_b32_e32 v150, 16, v166
	v_and_b32_e32 v151, 0xffff0000, v166
	v_lshlrev_b32_e32 v152, 16, v167
	v_and_b32_e32 v153, 0xffff0000, v167
	v_lshlrev_b32_e32 v154, 16, v168
	v_and_b32_e32 v155, 0xffff0000, v168
	v_lshlrev_b32_e32 v156, 16, v169
	v_and_b32_e32 v157, 0xffff0000, v169
	v_lshlrev_b32_e32 v158, 16, v170
	v_and_b32_e32 v159, 0xffff0000, v170
	v_lshlrev_b32_e32 v160, 16, v171
	v_and_b32_e32 v161, 0xffff0000, v171
	v_lshlrev_b32_e32 v162, 16, v172
	v_and_b32_e32 v163, 0xffff0000, v172
	v_lshlrev_b32_e32 v164, 16, v173
	v_and_b32_e32 v165, 0xffff0000, v173
	v_pk_fma_f32 v[28:29], v[28:29], v[150:151], v[158:159]
	v_pk_fma_f32 v[30:31], v[30:31], v[152:153], v[160:161]
	v_pk_fma_f32 v[164:165], v[26:27], v[156:157], v[164:165]
	v_pk_fma_f32 v[26:27], v[24:25], v[154:155], v[162:163]
	v_cvt_pk_bf16_f32 v24, v28, v29
	v_cvt_pk_bf16_f32 v25, v30, v31
	v_cvt_pk_bf16_f32 v26, v26, v27
	v_cvt_pk_bf16_f32 v27, v164, v165
	global_store_dwordx4 v[250:251], v[24:27], off
	v_lshlrev_b32_e32 v150, 16, v174
	v_and_b32_e32 v151, 0xffff0000, v174
	v_lshlrev_b32_e32 v152, 16, v175
	v_and_b32_e32 v153, 0xffff0000, v175
	v_lshlrev_b32_e32 v154, 16, v176
	v_and_b32_e32 v155, 0xffff0000, v176
	v_lshlrev_b32_e32 v156, 16, v177
	v_and_b32_e32 v157, 0xffff0000, v177
	v_lshlrev_b32_e32 v158, 16, v178
	v_and_b32_e32 v159, 0xffff0000, v178
	v_lshlrev_b32_e32 v160, 16, v179
	v_and_b32_e32 v161, 0xffff0000, v179
	v_lshlrev_b32_e32 v162, 16, v180
	v_and_b32_e32 v163, 0xffff0000, v180
	v_lshlrev_b32_e32 v164, 16, v181
	v_and_b32_e32 v165, 0xffff0000, v181
	v_pk_fma_f32 v[20:21], v[20:21], v[150:151], v[158:159]
	v_pk_fma_f32 v[22:23], v[22:23], v[152:153], v[160:161]
	v_pk_fma_f32 v[164:165], v[18:19], v[156:157], v[164:165]
	v_pk_fma_f32 v[18:19], v[16:17], v[154:155], v[162:163]
	v_cvt_pk_bf16_f32 v16, v20, v21
	v_cvt_pk_bf16_f32 v17, v22, v23
	v_cvt_pk_bf16_f32 v18, v18, v19
	v_cvt_pk_bf16_f32 v19, v164, v165
	global_store_dwordx4 v[250:251], v[16:19], off offset:256
	s_waitcnt vmcnt(4)
	v_lshlrev_b32_e32 v150, 16, v186
	v_and_b32_e32 v151, 0xffff0000, v186
	v_lshlrev_b32_e32 v152, 16, v187
	v_and_b32_e32 v153, 0xffff0000, v187
	v_lshlrev_b32_e32 v154, 16, v188
	v_and_b32_e32 v155, 0xffff0000, v188
	v_lshlrev_b32_e32 v156, 16, v189
	v_and_b32_e32 v157, 0xffff0000, v189
	v_lshlrev_b32_e32 v158, 16, v190
	v_and_b32_e32 v159, 0xffff0000, v190
	v_lshlrev_b32_e32 v160, 16, v191
	v_and_b32_e32 v161, 0xffff0000, v191
	v_lshlrev_b32_e32 v162, 16, v192
	v_and_b32_e32 v163, 0xffff0000, v192
	v_lshlrev_b32_e32 v164, 16, v193
	v_and_b32_e32 v165, 0xffff0000, v193
	v_pk_fma_f32 v[12:13], v[12:13], v[150:151], v[158:159]
	v_pk_fma_f32 v[14:15], v[14:15], v[152:153], v[160:161]
	v_pk_fma_f32 v[164:165], v[10:11], v[156:157], v[164:165]
	v_pk_fma_f32 v[10:11], v[8:9], v[154:155], v[162:163]
	v_cvt_pk_bf16_f32 v8, v12, v13
	v_cvt_pk_bf16_f32 v9, v14, v15
	v_cvt_pk_bf16_f32 v10, v10, v11
	v_cvt_pk_bf16_f32 v11, v164, v165
	global_store_dwordx4 v[242:243], v[8:11], off
	v_lshlrev_b32_e32 v150, 16, v194
	v_and_b32_e32 v151, 0xffff0000, v194
	v_lshlrev_b32_e32 v152, 16, v195
	v_and_b32_e32 v153, 0xffff0000, v195
	v_lshlrev_b32_e32 v154, 16, v196
	v_and_b32_e32 v155, 0xffff0000, v196
	v_lshlrev_b32_e32 v156, 16, v197
	v_and_b32_e32 v157, 0xffff0000, v197
	v_lshlrev_b32_e32 v158, 16, v222
	v_and_b32_e32 v159, 0xffff0000, v222
	v_lshlrev_b32_e32 v160, 16, v223
	v_and_b32_e32 v161, 0xffff0000, v223
	v_lshlrev_b32_e32 v162, 16, v224
	v_and_b32_e32 v163, 0xffff0000, v224
	v_lshlrev_b32_e32 v164, 16, v225
	v_and_b32_e32 v165, 0xffff0000, v225
	v_pk_fma_f32 v[4:5], v[4:5], v[150:151], v[158:159]
	v_pk_fma_f32 v[6:7], v[6:7], v[152:153], v[160:161]
	v_pk_fma_f32 v[164:165], v[2:3], v[156:157], v[164:165]
	v_pk_fma_f32 v[2:3], v[0:1], v[154:155], v[162:163]
	v_cvt_pk_bf16_f32 v0, v4, v5
	v_cvt_pk_bf16_f32 v1, v6, v7
	v_cvt_pk_bf16_f32 v2, v2, v3
	v_cvt_pk_bf16_f32 v3, v164, v165
	global_store_dwordx4 v[242:243], v[0:3], off offset:256
	s_cbranch_vccnz .LBB0_663
	s_andn2_b64 vcc, exec, s[8:9]
	s_cbranch_vccnz .LBB0_662
	s_barrier
	s_branch .LBB0_662

;     MI void operator()(const f32x4 (&acc)[2][2][4][2], const Unit& u, int wr, int wc, int fr, int fq) const {
;         const bool latent = u.pm < NT_LAT;
;         const float* base = latent ? bl + (size_t)u.pm * 256 * DM : bc + (size_t)(u.pm - NT_LAT) * 256 * DM; float* out = latent ? ol + (size_t)u.pm * 256 * DM : oc + (size_t)(u.pm - NT_LAT) * 256 * DM; const float* gt = latent ? gl : gc;
;         const int col = u.pn * 256 + wc * 32 + 4 * fq;
;         f32x4 gv[2][2];
; #pragma unroll
;         for (int bj = 0; bj < 2; ++bj)
; #pragma unroll
;             for (int n = 0; n < 2; ++n) gv[bj][n] = *(const f32x4*)(gt + col + bj * 128 + n * 16);
; #pragma unroll
;         for (int ai = 0; ai < 2; ++ai)
; #pragma unroll
;             for (int m = 0; m < 4; ++m) {
;                 const size_t off = (size_t)(ai * 128 + wr * 64 + m * 16 + fr) * DM + col;
; #pragma unroll
;                 for (int bj = 0; bj < 2; ++bj)
; #pragma unroll
;                     for (int n = 0; n < 2; ++n) { const f32x4 b = *(const f32x4*)(base + off + bj * 128 + n * 16); *(f32x4*)(out + off + bj * 128 + n * 16) = b + gv[bj][n] * acc[ai][bj][m][n]; }
.LBB0_937:
	s_sub_i32 s16, s76, 64
	s_ashr_i32 s17, s76, 31
	s_cmp_lt_i32 s76, 64
	v_readlane_b32 s22, v255, 23
	s_cselect_b32 s17, s17, 0
	s_cselect_b32 s16, s76, s16
	s_cselect_b32 s23, s56, s22
	v_readlane_b32 s22, v255, 22
	s_cselect_b32 s25, s52, s47
	s_cselect_b32 s58, s0, s1
	s_cselect_b32 s22, s55, s22
	s_lshl_b64 s[16:17], s[16:17], 21
	s_add_u32 s76, s58, s16
	v_lshl_or_b32 v56, s74, 8, v169
	s_addc_u32 s77, s25, s17
	v_ashrrev_i32_e32 v57, 31, v56
	v_lshlrev_b64 v[166:167], 2, v[56:57]
	v_lshl_add_u64 v[56:57], s[22:23], 0, v[166:167]
	global_load_dwordx4 v[120:123], v[56:57], off
	global_load_dwordx4 v[112:115], v[56:57], off offset:64
	global_load_dwordx4 v[108:111], v[56:57], off offset:512
	s_nop 0
	global_load_dwordx4 v[56:59], v[56:57], off offset:576
	s_mov_b64 s[22:23], -1
	s_andn2_b64 vcc, exec, s[4:5]
	s_mov_b64 s[82:83], s[40:41]
	v_lshl_add_u64 v[246:247], s[76:77], 0, v[146:147]
	v_lshl_add_u64 v[246:247], v[246:247], 0, v[166:167]
	global_load_dwordx4 v[172:175], v[246:247], off
	global_load_dwordx4 v[176:179], v[246:247], off offset:64
	global_load_dwordx4 v[180:183], v[246:247], off offset:512
	global_load_dwordx4 v[186:189], v[246:247], off offset:576
	v_lshl_add_u64 v[248:249], s[76:77], 0, v[156:157]
	v_lshl_add_u64 v[248:249], v[248:249], 0, v[166:167]
	global_load_dwordx4 v[190:193], v[248:249], off
	global_load_dwordx4 v[194:197], v[248:249], off offset:64
	global_load_dwordx4 v[222:225], v[248:249], off offset:512
	global_load_dwordx4 v[226:229], v[248:249], off offset:576
	v_lshl_add_u64 v[250:251], s[76:77], 0, v[158:159]
	v_lshl_add_u64 v[250:251], v[250:251], 0, v[166:167]
	global_load_dwordx4 v[230:233], v[250:251], off
	global_load_dwordx4 v[234:237], v[250:251], off offset:64
	global_load_dwordx4 v[238:241], v[250:251], off offset:512
	global_load_dwordx4 v[242:245], v[250:251], off offset:576
	s_waitcnt vmcnt(8)
	v_pk_fma_f32 v[142:143], v[142:143], v[122:123], v[174:175]
	v_pk_fma_f32 v[140:141], v[140:141], v[120:121], v[172:173]
	v_pk_fma_f32 v[138:139], v[138:139], v[114:115], v[178:179]
	v_pk_fma_f32 v[136:137], v[136:137], v[112:113], v[176:177]
	v_pk_fma_f32 v[134:135], v[134:135], v[110:111], v[182:183]
	v_pk_fma_f32 v[132:133], v[132:133], v[108:109], v[180:181]
	v_pk_fma_f32 v[126:127], v[126:127], v[58:59], v[188:189]
	v_pk_fma_f32 v[124:125], v[124:125], v[56:57], v[186:187]
	global_store_dwordx4 v[246:247], v[140:143], off
	global_store_dwordx4 v[246:247], v[136:139], off offset:64
	global_store_dwordx4 v[246:247], v[132:135], off offset:512
	global_store_dwordx4 v[246:247], v[124:127], off offset:576
	s_nop 1
	v_lshl_add_u64 v[246:247], s[76:77], 0, v[160:161]
	v_lshl_add_u64 v[246:247], v[246:247], 0, v[166:167]
	global_load_dwordx4 v[172:175], v[246:247], off
	global_load_dwordx4 v[176:179], v[246:247], off offset:64
	global_load_dwordx4 v[180:183], v[246:247], off offset:512
	global_load_dwordx4 v[186:189], v[246:247], off offset:576
	s_waitcnt vmcnt(12)
	v_pk_fma_f32 v[130:131], v[130:131], v[122:123], v[192:193]
	v_pk_fma_f32 v[128:129], v[128:129], v[120:121], v[190:191]
	v_pk_fma_f32 v[118:119], v[118:119], v[114:115], v[196:197]
	v_pk_fma_f32 v[116:117], v[116:117], v[112:113], v[194:195]
	v_pk_fma_f32 v[106:107], v[106:107], v[110:111], v[224:225]
	v_pk_fma_f32 v[104:105], v[104:105], v[108:109], v[222:223]
	v_pk_fma_f32 v[98:99], v[98:99], v[58:59], v[228:229]
	v_pk_fma_f32 v[96:97], v[96:97], v[56:57], v[226:227]
	global_store_dwordx4 v[248:249], v[128:131], off
	global_store_dwordx4 v[248:249], v[116:119], off offset:64
	global_store_dwordx4 v[248:249], v[104:107], off offset:512
	global_store_dwordx4 v[248:249], v[96:99], off offset:576
	s_nop 1
	v_lshl_add_u64 v[248:249], s[76:77], 0, v[148:149]
	v_lshl_add_u64 v[248:249], v[248:249], 0, v[166:167]
	global_load_dwordx4 v[190:193], v[248:249], off
	global_load_dwordx4 v[194:197], v[248:249], off offset:64
	global_load_dwordx4 v[222:225], v[248:249], off offset:512
	global_load_dwordx4 v[226:229], v[248:249], off offset:576
	s_waitcnt vmcnt(16)
	v_pk_fma_f32 v[102:103], v[102:103], v[122:123], v[232:233]
	v_pk_fma_f32 v[100:101], v[100:101], v[120:121], v[230:231]
	v_pk_fma_f32 v[94:95], v[94:95], v[114:115], v[236:237]
	v_pk_fma_f32 v[92:93], v[92:93], v[112:113], v[234:235]
	v_pk_fma_f32 v[90:91], v[90:91], v[110:111], v[240:241]
	v_pk_fma_f32 v[88:89], v[88:89], v[108:109], v[238:239]
	v_pk_fma_f32 v[82:83], v[82:83], v[58:59], v[244:245]
	v_pk_fma_f32 v[80:81], v[80:81], v[56:57], v[242:243]
	global_store_dwordx4 v[250:251], v[100:103], off
	global_store_dwordx4 v[250:251], v[92:95], off offset:64
	global_store_dwordx4 v[250:251], v[88:91], off offset:512
	global_store_dwordx4 v[250:251], v[80:83], off offset:576
	v_lshl_add_u64 v[250:251], s[76:77], 0, v[150:151]
	v_lshl_add_u64 v[250:251], v[250:251], 0, v[166:167]
	global_load_dwordx4 v[230:233], v[250:251], off
	global_load_dwordx4 v[234:237], v[250:251], off offset:64
	global_load_dwordx4 v[238:241], v[250:251], off offset:512
	global_load_dwordx4 v[242:245], v[250:251], off offset:576
	s_waitcnt vmcnt(16)
;     MI void operator()(const f32x4 (&acc)[2][2][4][2], const Unit& u, int wr, int wc, int fr, int fq) const {
;     ...
;         for (int ai = 0; ai < 2; ++ai)
; #pragma unroll
;             for (int m = 0; m < 4; ++m) {
;                 const size_t off = (size_t)(ai * 128 + wr * 64 + m * 16 + fr) * DM + col;
; #pragma unroll
;                 for (int bj = 0; bj < 2; ++bj)
; #pragma unroll
;                     for (int n = 0; n < 2; ++n) { const f32x4 b = *(const f32x4*)(base + off + bj * 128 + n * 16); *(f32x4*)(out + off + bj * 128 + n * 16) = b + gv[bj][n] * acc[ai][bj][m][n]; }
	v_pk_fma_f32 v[86:87], v[86:87], v[122:123], v[174:175]
	v_pk_fma_f32 v[84:85], v[84:85], v[120:121], v[172:173]
	v_pk_fma_f32 v[78:79], v[78:79], v[114:115], v[178:179]
	v_pk_fma_f32 v[76:77], v[76:77], v[112:113], v[176:177]
	v_pk_fma_f32 v[74:75], v[74:75], v[110:111], v[182:183]
	v_pk_fma_f32 v[72:73], v[72:73], v[108:109], v[180:181]
	v_pk_fma_f32 v[70:71], v[70:71], v[58:59], v[188:189]
	v_pk_fma_f32 v[68:69], v[68:69], v[56:57], v[186:187]
	global_store_dwordx4 v[246:247], v[84:87], off
	global_store_dwordx4 v[246:247], v[76:79], off offset:64
	global_store_dwordx4 v[246:247], v[72:75], off offset:512
	global_store_dwordx4 v[246:247], v[68:71], off offset:576
	s_nop 1
	v_lshl_add_u64 v[246:247], s[76:77], 0, v[152:153]
	v_lshl_add_u64 v[246:247], v[246:247], 0, v[166:167]
	global_load_dwordx4 v[172:175], v[246:247], off
	global_load_dwordx4 v[176:179], v[246:247], off offset:64
	global_load_dwordx4 v[180:183], v[246:247], off offset:512
	global_load_dwordx4 v[186:189], v[246:247], off offset:576
	s_waitcnt vmcnt(16)
	v_pk_fma_f32 v[66:67], v[66:67], v[122:123], v[192:193]
	v_pk_fma_f32 v[64:65], v[64:65], v[120:121], v[190:191]
	v_pk_fma_f32 v[62:63], v[62:63], v[114:115], v[196:197]
	v_pk_fma_f32 v[60:61], v[60:61], v[112:113], v[194:195]
	v_pk_fma_f32 v[54:55], v[54:55], v[110:111], v[224:225]
	v_pk_fma_f32 v[52:53], v[52:53], v[108:109], v[222:223]
	v_pk_fma_f32 v[50:51], v[50:51], v[58:59], v[228:229]
	v_pk_fma_f32 v[48:49], v[48:49], v[56:57], v[226:227]
	global_store_dwordx4 v[248:249], v[64:67], off
	global_store_dwordx4 v[248:249], v[60:63], off offset:64
	global_store_dwordx4 v[248:249], v[52:55], off offset:512
	global_store_dwordx4 v[248:249], v[48:51], off offset:576
	s_nop 1
	v_lshl_add_u64 v[248:249], s[76:77], 0, v[154:155]
	v_lshl_add_u64 v[248:249], v[248:249], 0, v[166:167]
	global_load_dwordx4 v[190:193], v[248:249], off
	global_load_dwordx4 v[194:197], v[248:249], off offset:64
	global_load_dwordx4 v[222:225], v[248:249], off offset:512
	global_load_dwordx4 v[226:229], v[248:249], off offset:576
	s_waitcnt vmcnt(16)
	v_pk_fma_f32 v[46:47], v[46:47], v[122:123], v[232:233]
	v_pk_fma_f32 v[44:45], v[44:45], v[120:121], v[230:231]
	v_pk_fma_f32 v[42:43], v[42:43], v[114:115], v[236:237]
	v_pk_fma_f32 v[40:41], v[40:41], v[112:113], v[234:235]
	v_pk_fma_f32 v[38:39], v[38:39], v[110:111], v[240:241]
	v_pk_fma_f32 v[36:37], v[36:37], v[108:109], v[238:239]
	v_pk_fma_f32 v[34:35], v[34:35], v[58:59], v[244:245]
	v_pk_fma_f32 v[32:33], v[32:33], v[56:57], v[242:243]
	global_store_dwordx4 v[250:251], v[44:47], off
	global_store_dwordx4 v[250:251], v[40:43], off offset:64
	global_store_dwordx4 v[250:251], v[36:39], off offset:512
	global_store_dwordx4 v[250:251], v[32:35], off offset:576
	s_waitcnt vmcnt(12)
	v_pk_fma_f32 v[30:31], v[30:31], v[122:123], v[174:175]
	v_pk_fma_f32 v[28:29], v[28:29], v[120:121], v[172:173]
	v_pk_fma_f32 v[26:27], v[26:27], v[114:115], v[178:179]
	v_pk_fma_f32 v[24:25], v[24:25], v[112:113], v[176:177]
	v_pk_fma_f32 v[22:23], v[22:23], v[110:111], v[182:183]
	v_pk_fma_f32 v[20:21], v[20:21], v[108:109], v[180:181]
	v_pk_fma_f32 v[18:19], v[18:19], v[58:59], v[188:189]
	v_pk_fma_f32 v[16:17], v[16:17], v[56:57], v[186:187]
	global_store_dwordx4 v[246:247], v[28:31], off
	global_store_dwordx4 v[246:247], v[24:27], off offset:64
	global_store_dwordx4 v[246:247], v[20:23], off offset:512
	global_store_dwordx4 v[246:247], v[16:19], off offset:576
	s_waitcnt vmcnt(8)
	v_pk_fma_f32 v[14:15], v[14:15], v[122:123], v[192:193]
	v_pk_fma_f32 v[12:13], v[12:13], v[120:121], v[190:191]
	v_pk_fma_f32 v[10:11], v[10:11], v[114:115], v[196:197]
	v_pk_fma_f32 v[8:9], v[8:9], v[112:113], v[194:195]
	v_pk_fma_f32 v[6:7], v[6:7], v[110:111], v[224:225]
	v_pk_fma_f32 v[4:5], v[4:5], v[108:109], v[222:223]
	v_pk_fma_f32 v[2:3], v[2:3], v[58:59], v[228:229]
	v_pk_fma_f32 v[0:1], v[0:1], v[56:57], v[226:227]
	global_store_dwordx4 v[248:249], v[12:15], off
	global_store_dwordx4 v[248:249], v[8:11], off offset:64
	global_store_dwordx4 v[248:249], v[4:7], off offset:512
	global_store_dwordx4 v[248:249], v[0:3], off offset:576
	s_cbranch_vccnz .LBB0_930
	s_andn2_b64 vcc, exec, s[6:7]
	s_cbranch_vccnz .LBB0_929
	s_barrier
	s_branch .LBB0_929
